# v44 + GEMM K-loops: removed no-op lgkmcnt(0) after s_setprio 1 and the back-to-back s_setprio 0/1 pairs inside the MFMA runs
# baseline (speedup 1.0000x reference)
; #define PG8_STAGE(bufoff, gbase, voff) do { _Pragma("unroll") for (int _i = 0; _i < 2; ++_i) \
;         __builtin_amdgcn_global_load_lds((const unsigned*)((const char*)(gbase) + (voff)[_i]), (PG8_LAS unsigned*)(lds + (bufoff) + ldsw + _i * 8192), 16, 0, 0); } while (0)
; #define PG8_LDA(dst, b, h) do { _Pragma("unroll") for (int m = 0; m < 4; ++m) _Pragma("unroll") for (int k = 0; k < 2; ++k) dst[m][k] = *(const PG8_LAS bf16x8*)(lds + PG8_SA(b, h) + aoff + m * 2048 + k * 1024); } while (0)
; #define PG8_LDB(dst, b, h) do { _Pragma("unroll") for (int n = 0; n < 2; ++n) _Pragma("unroll") for (int k = 0; k < 2; ++k) dst[n][k] = *(const PG8_LAS bf16x8*)(lds + PG8_SB(b, h) + boff + n * 2048 + k * 1024); } while (0)
; #define PG8_MMA(ai, bj, At, Bt) do { __builtin_amdgcn_s_setprio(1); _Pragma("unroll") for (int m = 0; m < 4; ++m) _Pragma("unroll") for (int n = 0; n < 2; ++n) _Pragma("unroll") for (int k = 0; k < 2; ++k) \
;         acc[ai][bj][m][n] = __builtin_amdgcn_mfma_f32_16x16x32_bf16(Bt[n][k], At[m][k], acc[ai][bj][m][n], 0, 0, 0); __builtin_amdgcn_s_setprio(0); } while (0)
; #define PG8_WAIT_V(n) asm volatile("s_waitcnt vmcnt(" #n ")" ::: "memory")
; #define PG8_WAIT_L(n) asm volatile("s_waitcnt lgkmcnt(" #n ")" ::: "memory")
; #define PG8_BAR __builtin_amdgcn_s_barrier()
; template <class Epi, class Sched, bool ALIGN_EPI = false, bool SP2 = false>
; __device__ __forceinline__ void gemm_phase(PG8_LAS unsigned char* lds, const Gemm g, const Sched& S, const Epi& E, int wv) {
;     ...
;             const char* a1 = cA + (size_t)(t + 1) * kstep;
;             const char* a2 = last ? nA : cA + (size_t)(t + 2) * kstep; const char* b2 = last ? nB : cB + (size_t)(t + 2) * kstep;
;             const char* a3 = a2 + kstep; const char* b3 = b2 + kstep;
;             if (last && has_next) S.a_ready(nxt);
;             if constexpr (SP2) {
;             PG8_LDB(B0, 0, 0); PG8_LDB(B1, 0, 1); PG8_SCHED; PG8_LDA(At, 0, 0); PG8_STAGE(PG8_SA(1, 1), a1 + hstepA, voffA);
;             PG8_WAIT_V(8); PG8_WAIT_L(0); PG8_BAR; PG8_MMA(0, 0, At, B0); PG8_MMA(0, 1, At, B1); PG8_BAR; PG8_SCHED;
;             PG8_LDA(At, 0, 1); PG8_STAGE(PG8_SB(0, 0), b2, voffB); PG8_STAGE(PG8_SB(0, 1), b2 + hstepB, voffB); PG8_STAGE(PG8_SA(0, 0), a2, voffA);
;             PG8_WAIT_V(8); PG8_WAIT_L(0); PG8_BAR; PG8_MMA(1, 0, At, B0); PG8_MMA(1, 1, At, B1); PG8_BAR; PG8_SCHED;
.LBB0_1645:
	s_waitcnt lgkmcnt(0)
	ds_read_b128 v[154:157], v182
	ds_read_b128 v[158:161], v182 offset:1024
	ds_read_b128 v[162:165], v182 offset:2048
	ds_read_b128 v[166:169], v182 offset:3072
	ds_read_b128 v[170:173], v183
	ds_read_b128 v[174:177], v183 offset:1024
	ds_read_b128 v[188:191], v183 offset:2048
	ds_read_b128 v[192:195], v183 offset:3072
	s_add_u32 s2, s8, 0xfffc0080
	s_addc_u32 s3, s9, -1
	s_cmp_eq_u32 vcc_lo, 12
	s_cselect_b32 s79, s7, s3
	s_cselect_b32 s78, s67, s2
	s_cselect_b32 s77, s69, s97
	s_cselect_b32 s76, s71, s96
	s_add_i32 m0, s83, 0xc000
	ds_read_b128 v[196:199], v184
	ds_read_b128 v[200:203], v184 offset:1024
	ds_read_b128 v[204:207], v184 offset:2048
	ds_read_b128 v[208:211], v184 offset:3072
	ds_read_b128 v[212:215], v184 offset:4096
	ds_read_b128 v[216:219], v184 offset:5120
	ds_read_b128 v[220:223], v184 offset:6144
	ds_read_b128 v[224:227], v184 offset:7168
	global_load_lds_dwordx4 v146, s[8:9]
	s_add_i32 m0, s83, 0xe000
	s_nop 0
	global_load_lds_dwordx4 v148, s[8:9]
	s_waitcnt vmcnt(8)
	s_waitcnt lgkmcnt(0)
	s_barrier
	s_setprio 1
	v_mfma_f32_16x16x32_bf16 v[124:127], v[154:157], v[196:199], v[124:127]
	v_mfma_f32_16x16x32_bf16 v[120:123], v[162:165], v[196:199], v[120:123]
	v_mfma_f32_16x16x32_bf16 v[108:111], v[154:157], v[204:207], v[108:111]
	v_mfma_f32_16x16x32_bf16 v[104:107], v[162:165], v[204:207], v[104:107]
	v_mfma_f32_16x16x32_bf16 v[92:95], v[154:157], v[212:215], v[92:95]
	v_mfma_f32_16x16x32_bf16 v[88:91], v[162:165], v[212:215], v[88:91]
	v_mfma_f32_16x16x32_bf16 v[76:79], v[154:157], v[220:223], v[76:79]
	v_mfma_f32_16x16x32_bf16 v[72:75], v[162:165], v[220:223], v[72:75]
	v_mfma_f32_16x16x32_bf16 v[124:127], v[158:161], v[200:203], v[124:127]
	v_mfma_f32_16x16x32_bf16 v[120:123], v[166:169], v[200:203], v[120:123]
	v_mfma_f32_16x16x32_bf16 v[108:111], v[158:161], v[208:211], v[108:111]
	v_mfma_f32_16x16x32_bf16 v[104:107], v[166:169], v[208:211], v[104:107]
	v_mfma_f32_16x16x32_bf16 v[92:95], v[158:161], v[216:219], v[92:95]
	v_mfma_f32_16x16x32_bf16 v[88:91], v[166:169], v[216:219], v[88:91]
	v_mfma_f32_16x16x32_bf16 v[76:79], v[158:161], v[224:227], v[76:79]
	v_mfma_f32_16x16x32_bf16 v[72:75], v[166:169], v[224:227], v[72:75]
	v_mfma_f32_16x16x32_bf16 v[116:119], v[170:173], v[196:199], v[116:119]
	v_mfma_f32_16x16x32_bf16 v[112:115], v[188:191], v[196:199], v[112:115]
	v_mfma_f32_16x16x32_bf16 v[100:103], v[170:173], v[204:207], v[100:103]
	v_mfma_f32_16x16x32_bf16 v[96:99], v[188:191], v[204:207], v[96:99]
	v_mfma_f32_16x16x32_bf16 v[84:87], v[170:173], v[212:215], v[84:87]
	v_mfma_f32_16x16x32_bf16 v[80:83], v[188:191], v[212:215], v[80:83]
	v_mfma_f32_16x16x32_bf16 v[68:71], v[170:173], v[220:223], v[68:71]
	v_mfma_f32_16x16x32_bf16 v[64:67], v[188:191], v[220:223], v[64:67]
	v_mfma_f32_16x16x32_bf16 v[116:119], v[174:177], v[200:203], v[116:119]
	v_mfma_f32_16x16x32_bf16 v[112:115], v[192:195], v[200:203], v[112:115]
	v_mfma_f32_16x16x32_bf16 v[100:103], v[174:177], v[208:211], v[100:103]
	v_mfma_f32_16x16x32_bf16 v[96:99], v[192:195], v[208:211], v[96:99]
	v_mfma_f32_16x16x32_bf16 v[84:87], v[174:177], v[216:219], v[84:87]
	v_mfma_f32_16x16x32_bf16 v[80:83], v[192:195], v[216:219], v[80:83]
	v_mfma_f32_16x16x32_bf16 v[68:71], v[174:177], v[224:227], v[68:71]
	v_mfma_f32_16x16x32_bf16 v[64:67], v[192:195], v[224:227], v[64:67]
	s_setprio 0
	s_barrier
	s_add_i32 s2, s91, s82
	s_mov_b32 m0, s2
	ds_read_b128 v[196:199], v184 offset:16384
	ds_read_b128 v[200:203], v184 offset:17408
	ds_read_b128 v[204:207], v184 offset:18432
	ds_read_b128 v[208:211], v184 offset:19456
	ds_read_b128 v[212:215], v184 offset:20480
	ds_read_b128 v[216:219], v184 offset:21504
	ds_read_b128 v[220:223], v184 offset:22528
	ds_read_b128 v[224:227], v184 offset:23552
	global_load_lds_dwordx4 v130, s[76:77]
	s_add_i32 m0, s2, 0x2000
	s_add_u32 s2, s76, 0x40000
	s_addc_u32 s3, s77, 0
	s_add_i32 vcc_hi, s92, s82
	global_load_lds_dwordx4 v134, s[76:77]
	s_mov_b32 m0, vcc_hi
	s_nop 0
	global_load_lds_dwordx4 v130, s[2:3]
	s_add_i32 m0, vcc_hi, 0x2000
	s_nop 0
	global_load_lds_dwordx4 v134, s[2:3]
	s_mov_b32 m0, s83
	s_nop 0
	global_load_lds_dwordx4 v128, s[78:79]
	s_mov_b32 m0, s84
	s_nop 0
	global_load_lds_dwordx4 v132, s[78:79]
	s_waitcnt vmcnt(8)
	s_waitcnt lgkmcnt(0)
	s_barrier
	s_setprio 1
	v_mfma_f32_16x16x32_bf16 v[60:63], v[154:157], v[196:199], v[60:63]
	v_mfma_f32_16x16x32_bf16 v[56:59], v[162:165], v[196:199], v[56:59]
	v_mfma_f32_16x16x32_bf16 v[44:47], v[154:157], v[204:207], v[44:47]
	v_mfma_f32_16x16x32_bf16 v[40:43], v[162:165], v[204:207], v[40:43]
	v_mfma_f32_16x16x32_bf16 v[28:31], v[154:157], v[212:215], v[28:31]
	v_mfma_f32_16x16x32_bf16 v[24:27], v[162:165], v[212:215], v[24:27]
	v_mfma_f32_16x16x32_bf16 v[12:15], v[154:157], v[220:223], v[12:15]
	v_mfma_f32_16x16x32_bf16 v[8:11], v[162:165], v[220:223], v[8:11]
	v_mfma_f32_16x16x32_bf16 v[60:63], v[158:161], v[200:203], v[60:63]
	v_mfma_f32_16x16x32_bf16 v[56:59], v[166:169], v[200:203], v[56:59]
	v_mfma_f32_16x16x32_bf16 v[44:47], v[158:161], v[208:211], v[44:47]
	v_mfma_f32_16x16x32_bf16 v[40:43], v[166:169], v[208:211], v[40:43]
	v_mfma_f32_16x16x32_bf16 v[28:31], v[158:161], v[216:219], v[28:31]
	v_mfma_f32_16x16x32_bf16 v[24:27], v[166:169], v[216:219], v[24:27]
	v_mfma_f32_16x16x32_bf16 v[12:15], v[158:161], v[224:227], v[12:15]
	v_mfma_f32_16x16x32_bf16 v[8:11], v[166:169], v[224:227], v[8:11]
	v_mfma_f32_16x16x32_bf16 v[52:55], v[170:173], v[196:199], v[52:55]
	v_mfma_f32_16x16x32_bf16 v[48:51], v[188:191], v[196:199], v[48:51]
	v_mfma_f32_16x16x32_bf16 v[36:39], v[170:173], v[204:207], v[36:39]
	v_mfma_f32_16x16x32_bf16 v[32:35], v[188:191], v[204:207], v[32:35]
	v_mfma_f32_16x16x32_bf16 v[20:23], v[170:173], v[212:215], v[20:23]
	v_mfma_f32_16x16x32_bf16 v[16:19], v[188:191], v[212:215], v[16:19]
	v_mfma_f32_16x16x32_bf16 v[4:7], v[170:173], v[220:223], v[4:7]
	v_mfma_f32_16x16x32_bf16 v[0:3], v[188:191], v[220:223], v[0:3]
	v_mfma_f32_16x16x32_bf16 v[52:55], v[174:177], v[200:203], v[52:55]
	v_mfma_f32_16x16x32_bf16 v[48:51], v[192:195], v[200:203], v[48:51]
	v_mfma_f32_16x16x32_bf16 v[36:39], v[174:177], v[208:211], v[36:39]
	v_mfma_f32_16x16x32_bf16 v[32:35], v[192:195], v[208:211], v[32:35]
	v_mfma_f32_16x16x32_bf16 v[20:23], v[174:177], v[216:219], v[20:23]
	v_mfma_f32_16x16x32_bf16 v[16:19], v[192:195], v[216:219], v[16:19]
	v_mfma_f32_16x16x32_bf16 v[4:7], v[174:177], v[224:227], v[4:7]
	v_mfma_f32_16x16x32_bf16 v[0:3], v[192:195], v[224:227], v[0:3]
	s_setprio 0
	s_barrier
; #define PG8_STAGE(bufoff, gbase, voff) do { _Pragma("unroll") for (int _i = 0; _i < 2; ++_i) \
;         __builtin_amdgcn_global_load_lds((const unsigned*)((const char*)(gbase) + (voff)[_i]), (PG8_LAS unsigned*)(lds + (bufoff) + ldsw + _i * 8192), 16, 0, 0); } while (0)
; #define PG8_LDA(dst, b, h) do { _Pragma("unroll") for (int m = 0; m < 4; ++m) _Pragma("unroll") for (int k = 0; k < 2; ++k) dst[m][k] = *(const PG8_LAS bf16x8*)(lds + PG8_SA(b, h) + aoff + m * 2048 + k * 1024); } while (0)
; #define PG8_LDB(dst, b, h) do { _Pragma("unroll") for (int n = 0; n < 2; ++n) _Pragma("unroll") for (int k = 0; k < 2; ++k) dst[n][k] = *(const PG8_LAS bf16x8*)(lds + PG8_SB(b, h) + boff + n * 2048 + k * 1024); } while (0)
; #define PG8_MMA(ai, bj, At, Bt) do { __builtin_amdgcn_s_setprio(1); _Pragma("unroll") for (int m = 0; m < 4; ++m) _Pragma("unroll") for (int n = 0; n < 2; ++n) _Pragma("unroll") for (int k = 0; k < 2; ++k) \
;         acc[ai][bj][m][n] = __builtin_amdgcn_mfma_f32_16x16x32_bf16(Bt[n][k], At[m][k], acc[ai][bj][m][n], 0, 0, 0); __builtin_amdgcn_s_setprio(0); } while (0)
; #define PG8_WAIT_V(n) asm volatile("s_waitcnt vmcnt(" #n ")" ::: "memory")
; #define PG8_WAIT_L(n) asm volatile("s_waitcnt lgkmcnt(" #n ")" ::: "memory")
; #define PG8_BAR __builtin_amdgcn_s_barrier()
; #define PG8_SCHED __builtin_amdgcn_sched_barrier(0)
; template <class Epi, class Sched, bool ALIGN_EPI = false, bool SP2 = false>
; __device__ __forceinline__ void gemm_phase(PG8_LAS unsigned char* lds, const Gemm g, const Sched& S, const Epi& E, int wv) {
;     ...
;             PG8_LDB(B0, 1, 0); PG8_LDB(B1, 1, 1); PG8_SCHED; PG8_LDA(At, 1, 0); PG8_STAGE(PG8_SA(0, 1), a2 + hstepA, voffA);
;             PG8_WAIT_V(8); PG8_WAIT_L(0); PG8_BAR; PG8_MMA(0, 0, At, B0); PG8_MMA(0, 1, At, B1); PG8_BAR; PG8_SCHED;
;             PG8_LDA(At, 1, 1); PG8_STAGE(PG8_SB(1, 0), b3, voffB); PG8_STAGE(PG8_SB(1, 1), b3 + hstepB, voffB); PG8_STAGE(PG8_SA(1, 0), a3, voffA);
;             PG8_WAIT_V(8); PG8_WAIT_L(0); PG8_BAR; PG8_MMA(1, 0, At, B0); PG8_MMA(1, 1, At, B1); PG8_BAR; PG8_SCHED;
;     ...
;         if constexpr (ALIGN_EPI) { if (wr == 0) PG8_BAR; }
	s_add_i32 vcc_hi, 0, 0x18000
	v_add_u32_e32 v136, vcc_hi, v178
	s_add_i32 s42, 0, 0x1c000
	ds_read_b128 v[154:157], v136
	ds_read_b128 v[158:161], v136 offset:1024
	ds_read_b128 v[162:165], v136 offset:2048
	ds_read_b128 v[166:169], v136 offset:3072
	v_add_u32_e32 v136, s42, v178
	ds_read_b128 v[170:173], v136
	ds_read_b128 v[174:177], v136 offset:1024
	ds_read_b128 v[188:191], v136 offset:2048
	ds_read_b128 v[192:195], v136 offset:3072
	s_add_u32 s2, s78, 0x40000
	s_addc_u32 s3, s79, 0
	s_mov_b32 m0, s85
	ds_read_b128 v[196:199], v184 offset:32768
	ds_read_b128 v[200:203], v184 offset:33792
	ds_read_b128 v[204:207], v184 offset:34816
	ds_read_b128 v[208:211], v184 offset:35840
	ds_read_b128 v[212:215], v184 offset:36864
	ds_read_b128 v[216:219], v184 offset:37888
	ds_read_b128 v[220:223], v184 offset:38912
	ds_read_b128 v[224:227], v184 offset:39936
	global_load_lds_dwordx4 v128, s[2:3]
	s_mov_b32 m0, s86
	s_nop 0
	global_load_lds_dwordx4 v132, s[2:3]
	s_waitcnt vmcnt(8)
	s_waitcnt lgkmcnt(0)
	s_barrier
	s_setprio 1
	v_mfma_f32_16x16x32_bf16 v[124:127], v[154:157], v[196:199], v[124:127]
	v_mfma_f32_16x16x32_bf16 v[120:123], v[162:165], v[196:199], v[120:123]
	v_mfma_f32_16x16x32_bf16 v[108:111], v[154:157], v[204:207], v[108:111]
	v_mfma_f32_16x16x32_bf16 v[104:107], v[162:165], v[204:207], v[104:107]
	v_mfma_f32_16x16x32_bf16 v[92:95], v[154:157], v[212:215], v[92:95]
	v_mfma_f32_16x16x32_bf16 v[88:91], v[162:165], v[212:215], v[88:91]
	v_mfma_f32_16x16x32_bf16 v[76:79], v[154:157], v[220:223], v[76:79]
	v_mfma_f32_16x16x32_bf16 v[72:75], v[162:165], v[220:223], v[72:75]
	v_mfma_f32_16x16x32_bf16 v[124:127], v[158:161], v[200:203], v[124:127]
	v_mfma_f32_16x16x32_bf16 v[120:123], v[166:169], v[200:203], v[120:123]
	v_mfma_f32_16x16x32_bf16 v[108:111], v[158:161], v[208:211], v[108:111]
	v_mfma_f32_16x16x32_bf16 v[104:107], v[166:169], v[208:211], v[104:107]
	v_mfma_f32_16x16x32_bf16 v[92:95], v[158:161], v[216:219], v[92:95]
	v_mfma_f32_16x16x32_bf16 v[88:91], v[166:169], v[216:219], v[88:91]
	v_mfma_f32_16x16x32_bf16 v[76:79], v[158:161], v[224:227], v[76:79]
	v_mfma_f32_16x16x32_bf16 v[72:75], v[166:169], v[224:227], v[72:75]
	v_mfma_f32_16x16x32_bf16 v[116:119], v[170:173], v[196:199], v[116:119]
	v_mfma_f32_16x16x32_bf16 v[112:115], v[188:191], v[196:199], v[112:115]
	v_mfma_f32_16x16x32_bf16 v[100:103], v[170:173], v[204:207], v[100:103]
	v_mfma_f32_16x16x32_bf16 v[96:99], v[188:191], v[204:207], v[96:99]
	v_mfma_f32_16x16x32_bf16 v[84:87], v[170:173], v[212:215], v[84:87]
	v_mfma_f32_16x16x32_bf16 v[80:83], v[188:191], v[212:215], v[80:83]
	v_mfma_f32_16x16x32_bf16 v[68:71], v[170:173], v[220:223], v[68:71]
	v_mfma_f32_16x16x32_bf16 v[64:67], v[188:191], v[220:223], v[64:67]
	v_mfma_f32_16x16x32_bf16 v[116:119], v[174:177], v[200:203], v[116:119]
	v_mfma_f32_16x16x32_bf16 v[112:115], v[192:195], v[200:203], v[112:115]
	v_mfma_f32_16x16x32_bf16 v[100:103], v[174:177], v[208:211], v[100:103]
	v_mfma_f32_16x16x32_bf16 v[96:99], v[192:195], v[208:211], v[96:99]
	v_mfma_f32_16x16x32_bf16 v[84:87], v[174:177], v[216:219], v[84:87]
	v_mfma_f32_16x16x32_bf16 v[80:83], v[192:195], v[216:219], v[80:83]
	v_mfma_f32_16x16x32_bf16 v[68:71], v[174:177], v[224:227], v[68:71]
	v_mfma_f32_16x16x32_bf16 v[64:67], v[192:195], v[224:227], v[64:67]
	s_setprio 0
	s_barrier
	s_add_i32 s2, vcc_hi, s82
	s_add_u32 s98, s76, 0x80
	s_addc_u32 s99, s77, 0
	s_mov_b32 m0, s2
	ds_read_b128 v[196:199], v184 offset:49152
	ds_read_b128 v[200:203], v184 offset:50176
	ds_read_b128 v[204:207], v184 offset:51200
	ds_read_b128 v[208:211], v184 offset:52224
	ds_read_b128 v[212:215], v184 offset:53248
	ds_read_b128 v[216:219], v184 offset:54272
	ds_read_b128 v[220:223], v184 offset:55296
	ds_read_b128 v[224:227], v184 offset:56320
	global_load_lds_dwordx4 v130, s[98:99]
	s_add_i32 m0, s2, 0x2000
	s_add_u32 s2, s76, 0x40080
	s_addc_u32 s3, s77, 0
	s_add_i32 s42, s42, s82
	global_load_lds_dwordx4 v134, s[98:99]
	s_mov_b32 m0, s42
	s_nop 0
	global_load_lds_dwordx4 v130, s[2:3]
	s_add_i32 m0, s42, 0x2000
	s_nop 0
	global_load_lds_dwordx4 v134, s[2:3]
	s_add_u32 s100, s78, 0x80
	s_addc_u32 s101, s79, 0
	s_mov_b32 m0, s87
	s_nop 0
	global_load_lds_dwordx4 v128, s[100:101]
	s_mov_b32 m0, s88
	s_nop 0
	global_load_lds_dwordx4 v132, s[100:101]
	s_waitcnt vmcnt(8)
	s_waitcnt lgkmcnt(0)
	s_barrier
	s_setprio 1
	v_mfma_f32_16x16x32_bf16 v[60:63], v[154:157], v[196:199], v[60:63]
	v_mfma_f32_16x16x32_bf16 v[56:59], v[162:165], v[196:199], v[56:59]
	v_mfma_f32_16x16x32_bf16 v[44:47], v[154:157], v[204:207], v[44:47]
	v_mfma_f32_16x16x32_bf16 v[40:43], v[162:165], v[204:207], v[40:43]
	v_mfma_f32_16x16x32_bf16 v[28:31], v[154:157], v[212:215], v[28:31]
	v_mfma_f32_16x16x32_bf16 v[24:27], v[162:165], v[212:215], v[24:27]
	v_mfma_f32_16x16x32_bf16 v[12:15], v[154:157], v[220:223], v[12:15]
	v_mfma_f32_16x16x32_bf16 v[8:11], v[162:165], v[220:223], v[8:11]
	v_mfma_f32_16x16x32_bf16 v[60:63], v[158:161], v[200:203], v[60:63]
	v_mfma_f32_16x16x32_bf16 v[56:59], v[166:169], v[200:203], v[56:59]
	v_mfma_f32_16x16x32_bf16 v[44:47], v[158:161], v[208:211], v[44:47]
	v_mfma_f32_16x16x32_bf16 v[40:43], v[166:169], v[208:211], v[40:43]
	v_mfma_f32_16x16x32_bf16 v[28:31], v[158:161], v[216:219], v[28:31]
	v_mfma_f32_16x16x32_bf16 v[24:27], v[166:169], v[216:219], v[24:27]
	v_mfma_f32_16x16x32_bf16 v[12:15], v[158:161], v[224:227], v[12:15]
	v_mfma_f32_16x16x32_bf16 v[8:11], v[166:169], v[224:227], v[8:11]
	v_mfma_f32_16x16x32_bf16 v[52:55], v[170:173], v[196:199], v[52:55]
	v_mfma_f32_16x16x32_bf16 v[48:51], v[188:191], v[196:199], v[48:51]
	v_mfma_f32_16x16x32_bf16 v[36:39], v[170:173], v[204:207], v[36:39]
	v_mfma_f32_16x16x32_bf16 v[32:35], v[188:191], v[204:207], v[32:35]
	v_mfma_f32_16x16x32_bf16 v[20:23], v[170:173], v[212:215], v[20:23]
	v_mfma_f32_16x16x32_bf16 v[16:19], v[188:191], v[212:215], v[16:19]
	v_mfma_f32_16x16x32_bf16 v[4:7], v[170:173], v[220:223], v[4:7]
	v_mfma_f32_16x16x32_bf16 v[0:3], v[188:191], v[220:223], v[0:3]
	v_mfma_f32_16x16x32_bf16 v[52:55], v[174:177], v[200:203], v[52:55]
	v_mfma_f32_16x16x32_bf16 v[48:51], v[192:195], v[200:203], v[48:51]
	v_mfma_f32_16x16x32_bf16 v[36:39], v[174:177], v[208:211], v[36:39]
	v_mfma_f32_16x16x32_bf16 v[32:35], v[192:195], v[208:211], v[32:35]
	v_mfma_f32_16x16x32_bf16 v[20:23], v[174:177], v[216:219], v[20:23]
	v_mfma_f32_16x16x32_bf16 v[16:19], v[192:195], v[216:219], v[16:19]
	v_mfma_f32_16x16x32_bf16 v[4:7], v[174:177], v[224:227], v[4:7]
	v_mfma_f32_16x16x32_bf16 v[0:3], v[192:195], v[224:227], v[0:3]
	s_setprio 0
	s_barrier
	s_add_i32 vcc_lo, vcc_lo, 2
	s_add_u32 s8, s8, 0x100
	s_addc_u32 s9, s9, 0
	s_add_u32 s96, s96, 0x100
	s_addc_u32 s97, s97, 0
	s_cmp_gt_u32 vcc_lo, 13
	s_cbranch_scc0 .LBB0_1645
	s_and_b64 vcc, exec, s[56:57]
	s_cbranch_vccz .LBB0_1648
	s_barrier

; #define PG8_STAGE(bufoff, gbase, voff) do { _Pragma("unroll") for (int _i = 0; _i < 2; ++_i) \
;         __builtin_amdgcn_global_load_lds((const unsigned*)((const char*)(gbase) + (voff)[_i]), (PG8_LAS unsigned*)(lds + (bufoff) + ldsw + _i * 8192), 16, 0, 0); } while (0)
; #define PG8_LDA(dst, b, h) do { _Pragma("unroll") for (int m = 0; m < 4; ++m) _Pragma("unroll") for (int k = 0; k < 2; ++k) dst[m][k] = *(const PG8_LAS bf16x8*)(lds + PG8_SA(b, h) + aoff + m * 2048 + k * 1024); } while (0)
; #define PG8_LDB(dst, b, h) do { _Pragma("unroll") for (int n = 0; n < 2; ++n) _Pragma("unroll") for (int k = 0; k < 2; ++k) dst[n][k] = *(const PG8_LAS bf16x8*)(lds + PG8_SB(b, h) + boff + n * 2048 + k * 1024); } while (0)
; #define PG8_MMA(ai, bj, At, Bt) do { __builtin_amdgcn_s_setprio(1); _Pragma("unroll") for (int m = 0; m < 4; ++m) _Pragma("unroll") for (int n = 0; n < 2; ++n) _Pragma("unroll") for (int k = 0; k < 2; ++k) \
;         acc[ai][bj][m][n] = __builtin_amdgcn_mfma_f32_16x16x32_bf16(Bt[n][k], At[m][k], acc[ai][bj][m][n], 0, 0, 0); __builtin_amdgcn_s_setprio(0); } while (0)
; #define PG8_WAIT_V(n) asm volatile("s_waitcnt vmcnt(" #n ")" ::: "memory")
; #define PG8_WAIT_L(n) asm volatile("s_waitcnt lgkmcnt(" #n ")" ::: "memory")
; #define PG8_BAR __builtin_amdgcn_s_barrier()
; template <class Epi, class Sched, bool ALIGN_EPI = false, bool SP2 = false>
; __device__ __forceinline__ void gemm_phase(PG8_LAS unsigned char* lds, const Gemm g, const Sched& S, const Epi& E, int wv) {
;     ...
;             const char* a1 = cA + (size_t)(t + 1) * kstep;
;             const char* a2 = last ? nA : cA + (size_t)(t + 2) * kstep; const char* b2 = last ? nB : cB + (size_t)(t + 2) * kstep;
;             const char* a3 = a2 + kstep; const char* b3 = b2 + kstep;
;             if (last && has_next) S.a_ready(nxt);
;             if constexpr (SP2) {
;             PG8_LDB(B0, 0, 0); PG8_LDB(B1, 0, 1); PG8_SCHED; PG8_LDA(At, 0, 0); PG8_STAGE(PG8_SA(1, 1), a1 + hstepA, voffA);
;             PG8_WAIT_V(8); PG8_WAIT_L(0); PG8_BAR; PG8_MMA(0, 0, At, B0); PG8_MMA(0, 1, At, B1); PG8_BAR; PG8_SCHED;
;             PG8_LDA(At, 0, 1); PG8_STAGE(PG8_SB(0, 0), b2, voffB); PG8_STAGE(PG8_SB(0, 1), b2 + hstepB, voffB); PG8_STAGE(PG8_SA(0, 0), a2, voffA);
;             PG8_WAIT_V(8); PG8_WAIT_L(0); PG8_BAR; PG8_MMA(1, 0, At, B0); PG8_MMA(1, 1, At, B1); PG8_BAR; PG8_SCHED;
.LBB0_1787:
	ds_read_b128 v[152:155], v164
	ds_read_b128 v[156:159], v164 offset:1024
	ds_read_b128 v[160:163], v164 offset:2048
	ds_read_b128 v[168:171], v164 offset:3072
	ds_read_b128 v[172:175], v165
	ds_read_b128 v[176:179], v165 offset:1024
	ds_read_b128 v[180:183], v165 offset:2048
	ds_read_b128 v[184:187], v165 offset:3072
	s_add_i32 s1, s0, 2
	s_add_u32 s2, s6, 0x80
	s_addc_u32 s3, s7, 0
	s_cmp_eq_u32 s80, s0
	s_cselect_b32 s9, s45, s3
	s_cselect_b32 s8, s44, s2
	s_cselect_b32 s3, s61, s13
	s_cselect_b32 s2, s60, s12
	v_lshl_add_u64 v[220:221], s[6:7], 0, v[146:147]
	s_add_i32 m0, s71, 0xc000
	ds_read_b128 v[188:191], v166
	ds_read_b128 v[192:195], v166 offset:1024
	ds_read_b128 v[196:199], v166 offset:2048
	ds_read_b128 v[200:203], v166 offset:3072
	ds_read_b128 v[204:207], v166 offset:4096
	ds_read_b128 v[208:211], v166 offset:5120
	ds_read_b128 v[212:215], v166 offset:6144
	ds_read_b128 v[216:219], v166 offset:7168
	global_load_lds_dwordx4 v[220:221], off
	v_lshl_add_u64 v[220:221], s[6:7], 0, v[148:149]
	s_add_i32 m0, s71, 0xe000
	s_nop 0
	global_load_lds_dwordx4 v[220:221], off
	s_waitcnt vmcnt(8)
	s_waitcnt lgkmcnt(0)
	s_barrier
	s_setprio 1
	v_mfma_f32_16x16x32_bf16 v[124:127], v[152:155], v[188:191], v[124:127]
	v_mfma_f32_16x16x32_bf16 v[120:123], v[160:163], v[188:191], v[120:123]
	v_mfma_f32_16x16x32_bf16 v[108:111], v[152:155], v[196:199], v[108:111]
	v_mfma_f32_16x16x32_bf16 v[104:107], v[160:163], v[196:199], v[104:107]
	v_mfma_f32_16x16x32_bf16 v[92:95], v[152:155], v[204:207], v[92:95]
	v_mfma_f32_16x16x32_bf16 v[88:91], v[160:163], v[204:207], v[88:91]
	v_mfma_f32_16x16x32_bf16 v[76:79], v[152:155], v[212:215], v[76:79]
	v_mfma_f32_16x16x32_bf16 v[72:75], v[160:163], v[212:215], v[72:75]
	v_mfma_f32_16x16x32_bf16 v[124:127], v[156:159], v[192:195], v[124:127]
	v_mfma_f32_16x16x32_bf16 v[120:123], v[168:171], v[192:195], v[120:123]
	v_mfma_f32_16x16x32_bf16 v[108:111], v[156:159], v[200:203], v[108:111]
	v_mfma_f32_16x16x32_bf16 v[104:107], v[168:171], v[200:203], v[104:107]
	v_mfma_f32_16x16x32_bf16 v[92:95], v[156:159], v[208:211], v[92:95]
	v_mfma_f32_16x16x32_bf16 v[88:91], v[168:171], v[208:211], v[88:91]
	v_mfma_f32_16x16x32_bf16 v[76:79], v[156:159], v[216:219], v[76:79]
	v_mfma_f32_16x16x32_bf16 v[72:75], v[168:171], v[216:219], v[72:75]
	v_mfma_f32_16x16x32_bf16 v[116:119], v[172:175], v[188:191], v[116:119]
	v_mfma_f32_16x16x32_bf16 v[112:115], v[180:183], v[188:191], v[112:115]
	v_mfma_f32_16x16x32_bf16 v[100:103], v[172:175], v[196:199], v[100:103]
	v_mfma_f32_16x16x32_bf16 v[96:99], v[180:183], v[196:199], v[96:99]
	v_mfma_f32_16x16x32_bf16 v[84:87], v[172:175], v[204:207], v[84:87]
	v_mfma_f32_16x16x32_bf16 v[80:83], v[180:183], v[204:207], v[80:83]
	v_mfma_f32_16x16x32_bf16 v[68:71], v[172:175], v[212:215], v[68:71]
	v_mfma_f32_16x16x32_bf16 v[64:67], v[180:183], v[212:215], v[64:67]
	v_mfma_f32_16x16x32_bf16 v[116:119], v[176:179], v[192:195], v[116:119]
	v_mfma_f32_16x16x32_bf16 v[112:115], v[184:187], v[192:195], v[112:115]
	v_mfma_f32_16x16x32_bf16 v[100:103], v[176:179], v[200:203], v[100:103]
	v_mfma_f32_16x16x32_bf16 v[96:99], v[184:187], v[200:203], v[96:99]
	v_mfma_f32_16x16x32_bf16 v[84:87], v[176:179], v[208:211], v[84:87]
	v_mfma_f32_16x16x32_bf16 v[80:83], v[184:187], v[208:211], v[80:83]
	v_mfma_f32_16x16x32_bf16 v[68:71], v[176:179], v[216:219], v[68:71]
	v_mfma_f32_16x16x32_bf16 v[64:67], v[184:187], v[216:219], v[64:67]
	s_setprio 0
	s_barrier
	s_add_i32 s0, s88, s70
	v_lshl_add_u64 v[220:221], s[2:3], 0, v[130:131]
	s_mov_b32 m0, s0
	ds_read_b128 v[188:191], v166 offset:16384
	ds_read_b128 v[192:195], v166 offset:17408
	ds_read_b128 v[196:199], v166 offset:18432
	ds_read_b128 v[200:203], v166 offset:19456
	ds_read_b128 v[204:207], v166 offset:20480
	ds_read_b128 v[208:211], v166 offset:21504
	ds_read_b128 v[212:215], v166 offset:22528
	ds_read_b128 v[216:219], v166 offset:23552
	global_load_lds_dwordx4 v[220:221], off
	s_add_i32 m0, s0, 0x2000
	v_lshl_add_u64 v[222:223], s[2:3], 0, v[134:135]
	s_add_u32 s2, s2, s40
	s_addc_u32 s3, s3, s41
	s_add_i32 s0, s89, s70
	global_load_lds_dwordx4 v[222:223], off
	v_lshl_add_u64 v[224:225], s[2:3], 0, v[130:131]
	s_mov_b32 m0, s0
	v_lshl_add_u64 v[226:227], s[2:3], 0, v[134:135]
	global_load_lds_dwordx4 v[224:225], off
	s_add_i32 m0, s0, 0x2000
	v_lshl_add_u64 v[228:229], s[8:9], 0, v[128:129]
	global_load_lds_dwordx4 v[226:227], off
	s_mov_b32 m0, s71
	v_lshl_add_u64 v[230:231], s[8:9], 0, v[132:133]
	global_load_lds_dwordx4 v[228:229], off
	s_mov_b32 m0, s72
	s_nop 0
	global_load_lds_dwordx4 v[230:231], off
	s_waitcnt vmcnt(8)
	s_waitcnt lgkmcnt(0)
	s_barrier
; #define PG8_STAGE(bufoff, gbase, voff) do { _Pragma("unroll") for (int _i = 0; _i < 2; ++_i) \
;         __builtin_amdgcn_global_load_lds((const unsigned*)((const char*)(gbase) + (voff)[_i]), (PG8_LAS unsigned*)(lds + (bufoff) + ldsw + _i * 8192), 16, 0, 0); } while (0)
; #define PG8_LDA(dst, b, h) do { _Pragma("unroll") for (int m = 0; m < 4; ++m) _Pragma("unroll") for (int k = 0; k < 2; ++k) dst[m][k] = *(const PG8_LAS bf16x8*)(lds + PG8_SA(b, h) + aoff + m * 2048 + k * 1024); } while (0)
; #define PG8_LDB(dst, b, h) do { _Pragma("unroll") for (int n = 0; n < 2; ++n) _Pragma("unroll") for (int k = 0; k < 2; ++k) dst[n][k] = *(const PG8_LAS bf16x8*)(lds + PG8_SB(b, h) + boff + n * 2048 + k * 1024); } while (0)
; #define PG8_MMA(ai, bj, At, Bt) do { __builtin_amdgcn_s_setprio(1); _Pragma("unroll") for (int m = 0; m < 4; ++m) _Pragma("unroll") for (int n = 0; n < 2; ++n) _Pragma("unroll") for (int k = 0; k < 2; ++k) \
;         acc[ai][bj][m][n] = __builtin_amdgcn_mfma_f32_16x16x32_bf16(Bt[n][k], At[m][k], acc[ai][bj][m][n], 0, 0, 0); __builtin_amdgcn_s_setprio(0); } while (0)
; #define PG8_WAIT_V(n) asm volatile("s_waitcnt vmcnt(" #n ")" ::: "memory")
; #define PG8_WAIT_L(n) asm volatile("s_waitcnt lgkmcnt(" #n ")" ::: "memory")
; #define PG8_BAR __builtin_amdgcn_s_barrier()
; #define PG8_SCHED __builtin_amdgcn_sched_barrier(0)
; template <class Epi, class Sched, bool ALIGN_EPI = false, bool SP2 = false>
; __device__ __forceinline__ void gemm_phase(PG8_LAS unsigned char* lds, const Gemm g, const Sched& S, const Epi& E, int wv) {
;     ...
;             PG8_WAIT_V(8); PG8_WAIT_L(0); PG8_BAR; PG8_MMA(1, 0, At, B0); PG8_MMA(1, 1, At, B1); PG8_BAR; PG8_SCHED;
;             PG8_LDB(B0, 1, 0); PG8_LDB(B1, 1, 1); PG8_SCHED; PG8_LDA(At, 1, 0); PG8_STAGE(PG8_SA(0, 1), a2 + hstepA, voffA);
;             PG8_WAIT_V(8); PG8_WAIT_L(0); PG8_BAR; PG8_MMA(0, 0, At, B0); PG8_MMA(0, 1, At, B1); PG8_BAR; PG8_SCHED;
	s_setprio 1
	v_mfma_f32_16x16x32_bf16 v[60:63], v[152:155], v[188:191], v[60:63]
	v_mfma_f32_16x16x32_bf16 v[56:59], v[160:163], v[188:191], v[56:59]
	v_mfma_f32_16x16x32_bf16 v[44:47], v[152:155], v[196:199], v[44:47]
	v_mfma_f32_16x16x32_bf16 v[40:43], v[160:163], v[196:199], v[40:43]
	v_mfma_f32_16x16x32_bf16 v[28:31], v[152:155], v[204:207], v[28:31]
	v_mfma_f32_16x16x32_bf16 v[24:27], v[160:163], v[204:207], v[24:27]
	v_mfma_f32_16x16x32_bf16 v[12:15], v[152:155], v[212:215], v[12:15]
	v_mfma_f32_16x16x32_bf16 v[8:11], v[160:163], v[212:215], v[8:11]
	v_mfma_f32_16x16x32_bf16 v[60:63], v[156:159], v[192:195], v[60:63]
	v_mfma_f32_16x16x32_bf16 v[56:59], v[168:171], v[192:195], v[56:59]
	v_mfma_f32_16x16x32_bf16 v[44:47], v[156:159], v[200:203], v[44:47]
	v_mfma_f32_16x16x32_bf16 v[40:43], v[168:171], v[200:203], v[40:43]
	v_mfma_f32_16x16x32_bf16 v[28:31], v[156:159], v[208:211], v[28:31]
	v_mfma_f32_16x16x32_bf16 v[24:27], v[168:171], v[208:211], v[24:27]
	v_mfma_f32_16x16x32_bf16 v[12:15], v[156:159], v[216:219], v[12:15]
	v_mfma_f32_16x16x32_bf16 v[8:11], v[168:171], v[216:219], v[8:11]
	v_mfma_f32_16x16x32_bf16 v[52:55], v[172:175], v[188:191], v[52:55]
	v_mfma_f32_16x16x32_bf16 v[48:51], v[180:183], v[188:191], v[48:51]
	v_mfma_f32_16x16x32_bf16 v[36:39], v[172:175], v[196:199], v[36:39]
	v_mfma_f32_16x16x32_bf16 v[32:35], v[180:183], v[196:199], v[32:35]
	v_mfma_f32_16x16x32_bf16 v[20:23], v[172:175], v[204:207], v[20:23]
	v_mfma_f32_16x16x32_bf16 v[16:19], v[180:183], v[204:207], v[16:19]
	v_mfma_f32_16x16x32_bf16 v[4:7], v[172:175], v[212:215], v[4:7]
	v_mfma_f32_16x16x32_bf16 v[0:3], v[180:183], v[212:215], v[0:3]
	v_mfma_f32_16x16x32_bf16 v[52:55], v[176:179], v[192:195], v[52:55]
	v_mfma_f32_16x16x32_bf16 v[48:51], v[184:187], v[192:195], v[48:51]
	v_mfma_f32_16x16x32_bf16 v[36:39], v[176:179], v[200:203], v[36:39]
	v_mfma_f32_16x16x32_bf16 v[32:35], v[184:187], v[200:203], v[32:35]
	v_mfma_f32_16x16x32_bf16 v[20:23], v[176:179], v[208:211], v[20:23]
	v_mfma_f32_16x16x32_bf16 v[16:19], v[184:187], v[208:211], v[16:19]
	v_mfma_f32_16x16x32_bf16 v[4:7], v[176:179], v[216:219], v[4:7]
	v_mfma_f32_16x16x32_bf16 v[0:3], v[184:187], v[216:219], v[0:3]
	s_setprio 0
	s_barrier
	s_add_i32 s0, 0, 0x18000
	v_add_u32_e32 v136, s0, v141
	s_add_i32 s42, 0, 0x1c000
	ds_read_b128 v[152:155], v136
	ds_read_b128 v[156:159], v136 offset:1024
	ds_read_b128 v[160:163], v136 offset:2048
	ds_read_b128 v[168:171], v136 offset:3072
	v_add_u32_e32 v136, s42, v141
	ds_read_b128 v[172:175], v136
	ds_read_b128 v[176:179], v136 offset:1024
	ds_read_b128 v[180:183], v136 offset:2048
	ds_read_b128 v[184:187], v136 offset:3072
	s_add_u32 s2, s8, s38
	s_addc_u32 s3, s9, s39
	s_mov_b32 m0, s73
	v_lshl_add_u64 v[232:233], s[2:3], 0, v[128:129]
	ds_read_b128 v[188:191], v166 offset:32768
	ds_read_b128 v[192:195], v166 offset:33792
	ds_read_b128 v[196:199], v166 offset:34816
	ds_read_b128 v[200:203], v166 offset:35840
	ds_read_b128 v[204:207], v166 offset:36864
	ds_read_b128 v[208:211], v166 offset:37888
	ds_read_b128 v[212:215], v166 offset:38912
	ds_read_b128 v[216:219], v166 offset:39936
	global_load_lds_dwordx4 v[232:233], off
	v_lshl_add_u64 v[232:233], s[2:3], 0, v[132:133]
	s_mov_b32 m0, s74
	s_nop 0
	global_load_lds_dwordx4 v[232:233], off
	s_waitcnt vmcnt(8)
	s_waitcnt lgkmcnt(0)
	s_barrier
	s_setprio 1
	v_mfma_f32_16x16x32_bf16 v[124:127], v[152:155], v[188:191], v[124:127]
	v_mfma_f32_16x16x32_bf16 v[120:123], v[160:163], v[188:191], v[120:123]
	v_mfma_f32_16x16x32_bf16 v[108:111], v[152:155], v[196:199], v[108:111]
	v_mfma_f32_16x16x32_bf16 v[104:107], v[160:163], v[196:199], v[104:107]
	v_mfma_f32_16x16x32_bf16 v[92:95], v[152:155], v[204:207], v[92:95]
	v_mfma_f32_16x16x32_bf16 v[88:91], v[160:163], v[204:207], v[88:91]
	v_mfma_f32_16x16x32_bf16 v[76:79], v[152:155], v[212:215], v[76:79]
	v_mfma_f32_16x16x32_bf16 v[72:75], v[160:163], v[212:215], v[72:75]
	v_mfma_f32_16x16x32_bf16 v[124:127], v[156:159], v[192:195], v[124:127]
	v_mfma_f32_16x16x32_bf16 v[120:123], v[168:171], v[192:195], v[120:123]
	v_mfma_f32_16x16x32_bf16 v[108:111], v[156:159], v[200:203], v[108:111]
	v_mfma_f32_16x16x32_bf16 v[104:107], v[168:171], v[200:203], v[104:107]
	v_mfma_f32_16x16x32_bf16 v[92:95], v[156:159], v[208:211], v[92:95]
	v_mfma_f32_16x16x32_bf16 v[88:91], v[168:171], v[208:211], v[88:91]
	v_mfma_f32_16x16x32_bf16 v[76:79], v[156:159], v[216:219], v[76:79]
	v_mfma_f32_16x16x32_bf16 v[72:75], v[168:171], v[216:219], v[72:75]
	v_mfma_f32_16x16x32_bf16 v[116:119], v[172:175], v[188:191], v[116:119]
	v_mfma_f32_16x16x32_bf16 v[112:115], v[180:183], v[188:191], v[112:115]
	v_mfma_f32_16x16x32_bf16 v[100:103], v[172:175], v[196:199], v[100:103]
	v_mfma_f32_16x16x32_bf16 v[96:99], v[180:183], v[196:199], v[96:99]
	v_mfma_f32_16x16x32_bf16 v[84:87], v[172:175], v[204:207], v[84:87]
	v_mfma_f32_16x16x32_bf16 v[80:83], v[180:183], v[204:207], v[80:83]
	v_mfma_f32_16x16x32_bf16 v[68:71], v[172:175], v[212:215], v[68:71]
	v_mfma_f32_16x16x32_bf16 v[64:67], v[180:183], v[212:215], v[64:67]
	v_mfma_f32_16x16x32_bf16 v[116:119], v[176:179], v[192:195], v[116:119]
	v_mfma_f32_16x16x32_bf16 v[112:115], v[184:187], v[192:195], v[112:115]
	v_mfma_f32_16x16x32_bf16 v[100:103], v[176:179], v[200:203], v[100:103]
	v_mfma_f32_16x16x32_bf16 v[96:99], v[184:187], v[200:203], v[96:99]
	v_mfma_f32_16x16x32_bf16 v[84:87], v[176:179], v[208:211], v[84:87]
	v_mfma_f32_16x16x32_bf16 v[80:83], v[184:187], v[208:211], v[80:83]
	v_mfma_f32_16x16x32_bf16 v[68:71], v[176:179], v[216:219], v[68:71]
	v_mfma_f32_16x16x32_bf16 v[64:67], v[184:187], v[216:219], v[64:67]
	s_setprio 0
	s_barrier
; #define PG8_STAGE(bufoff, gbase, voff) do { _Pragma("unroll") for (int _i = 0; _i < 2; ++_i) \
;         __builtin_amdgcn_global_load_lds((const unsigned*)((const char*)(gbase) + (voff)[_i]), (PG8_LAS unsigned*)(lds + (bufoff) + ldsw + _i * 8192), 16, 0, 0); } while (0)
; #define PG8_LDA(dst, b, h) do { _Pragma("unroll") for (int m = 0; m < 4; ++m) _Pragma("unroll") for (int k = 0; k < 2; ++k) dst[m][k] = *(const PG8_LAS bf16x8*)(lds + PG8_SA(b, h) + aoff + m * 2048 + k * 1024); } while (0)
; #define PG8_MMA(ai, bj, At, Bt) do { __builtin_amdgcn_s_setprio(1); _Pragma("unroll") for (int m = 0; m < 4; ++m) _Pragma("unroll") for (int n = 0; n < 2; ++n) _Pragma("unroll") for (int k = 0; k < 2; ++k) \
;         acc[ai][bj][m][n] = __builtin_amdgcn_mfma_f32_16x16x32_bf16(Bt[n][k], At[m][k], acc[ai][bj][m][n], 0, 0, 0); __builtin_amdgcn_s_setprio(0); } while (0)
; #define PG8_WAIT_V(n) asm volatile("s_waitcnt vmcnt(" #n ")" ::: "memory")
; #define PG8_WAIT_L(n) asm volatile("s_waitcnt lgkmcnt(" #n ")" ::: "memory")
; #define PG8_BAR __builtin_amdgcn_s_barrier()
; #define PG8_SCHED __builtin_amdgcn_sched_barrier(0)
; template <class Epi, class Sched, bool ALIGN_EPI = false, bool SP2 = false>
; __device__ __forceinline__ void gemm_phase(PG8_LAS unsigned char* lds, const Gemm g, const Sched& S, const Epi& E, int wv) {
;     ...
;         for (int t = 0; t < nt; t += 2) {
;     ...
;             PG8_LDA(At, 1, 1); PG8_STAGE(PG8_SB(1, 0), b3, voffB); PG8_STAGE(PG8_SB(1, 1), b3 + hstepB, voffB); PG8_STAGE(PG8_SA(1, 0), a3, voffA);
;             PG8_WAIT_V(8); PG8_WAIT_L(0); PG8_BAR; PG8_MMA(1, 0, At, B0); PG8_MMA(1, 1, At, B1); PG8_BAR; PG8_SCHED;
	s_add_i32 s0, s0, s70
	v_lshl_add_u64 v[220:221], v[220:221], 0, s[54:55]
	s_mov_b32 m0, s0
	ds_read_b128 v[188:191], v166 offset:49152
	ds_read_b128 v[192:195], v166 offset:50176
	ds_read_b128 v[196:199], v166 offset:51200
	ds_read_b128 v[200:203], v166 offset:52224
	ds_read_b128 v[204:207], v166 offset:53248
	ds_read_b128 v[208:211], v166 offset:54272
	ds_read_b128 v[212:215], v166 offset:55296
	ds_read_b128 v[216:219], v166 offset:56320
	global_load_lds_dwordx4 v[220:221], off
	v_lshl_add_u64 v[220:221], v[222:223], 0, s[54:55]
	s_add_i32 m0, s0, 0x2000
	s_add_i32 s0, s42, s70
	global_load_lds_dwordx4 v[220:221], off
	v_lshl_add_u64 v[220:221], v[224:225], 0, s[54:55]
	s_mov_b32 m0, s0
	s_nop 0
	global_load_lds_dwordx4 v[220:221], off
	v_lshl_add_u64 v[220:221], v[226:227], 0, s[54:55]
	s_add_i32 m0, s0, 0x2000
	s_nop 0
	global_load_lds_dwordx4 v[220:221], off
	v_lshl_add_u64 v[220:221], v[228:229], 0, s[54:55]
	s_mov_b32 m0, s76
	s_nop 0
	global_load_lds_dwordx4 v[220:221], off
	v_lshl_add_u64 v[220:221], v[230:231], 0, s[54:55]
	s_mov_b32 m0, s77
	s_nop 0
	global_load_lds_dwordx4 v[220:221], off
	s_waitcnt vmcnt(8)
	s_waitcnt lgkmcnt(0)
	s_barrier
	s_setprio 1
	v_mfma_f32_16x16x32_bf16 v[60:63], v[152:155], v[188:191], v[60:63]
	v_mfma_f32_16x16x32_bf16 v[56:59], v[160:163], v[188:191], v[56:59]
	v_mfma_f32_16x16x32_bf16 v[44:47], v[152:155], v[196:199], v[44:47]
	v_mfma_f32_16x16x32_bf16 v[40:43], v[160:163], v[196:199], v[40:43]
	v_mfma_f32_16x16x32_bf16 v[28:31], v[152:155], v[204:207], v[28:31]
	v_mfma_f32_16x16x32_bf16 v[24:27], v[160:163], v[204:207], v[24:27]
	v_mfma_f32_16x16x32_bf16 v[12:15], v[152:155], v[212:215], v[12:15]
	v_mfma_f32_16x16x32_bf16 v[8:11], v[160:163], v[212:215], v[8:11]
	v_mfma_f32_16x16x32_bf16 v[60:63], v[156:159], v[192:195], v[60:63]
	v_mfma_f32_16x16x32_bf16 v[56:59], v[168:171], v[192:195], v[56:59]
	v_mfma_f32_16x16x32_bf16 v[44:47], v[156:159], v[200:203], v[44:47]
	v_mfma_f32_16x16x32_bf16 v[40:43], v[168:171], v[200:203], v[40:43]
	v_mfma_f32_16x16x32_bf16 v[28:31], v[156:159], v[208:211], v[28:31]
	v_mfma_f32_16x16x32_bf16 v[24:27], v[168:171], v[208:211], v[24:27]
	v_mfma_f32_16x16x32_bf16 v[12:15], v[156:159], v[216:219], v[12:15]
	v_mfma_f32_16x16x32_bf16 v[8:11], v[168:171], v[216:219], v[8:11]
	v_mfma_f32_16x16x32_bf16 v[52:55], v[172:175], v[188:191], v[52:55]
	v_mfma_f32_16x16x32_bf16 v[48:51], v[180:183], v[188:191], v[48:51]
	v_mfma_f32_16x16x32_bf16 v[36:39], v[172:175], v[196:199], v[36:39]
	v_mfma_f32_16x16x32_bf16 v[32:35], v[180:183], v[196:199], v[32:35]
	v_mfma_f32_16x16x32_bf16 v[20:23], v[172:175], v[204:207], v[20:23]
	v_mfma_f32_16x16x32_bf16 v[16:19], v[180:183], v[204:207], v[16:19]
	v_mfma_f32_16x16x32_bf16 v[4:7], v[172:175], v[212:215], v[4:7]
	v_mfma_f32_16x16x32_bf16 v[0:3], v[180:183], v[212:215], v[0:3]
	v_mfma_f32_16x16x32_bf16 v[52:55], v[176:179], v[192:195], v[52:55]
	v_mfma_f32_16x16x32_bf16 v[48:51], v[184:187], v[192:195], v[48:51]
	v_mfma_f32_16x16x32_bf16 v[36:39], v[176:179], v[200:203], v[36:39]
	v_mfma_f32_16x16x32_bf16 v[32:35], v[184:187], v[200:203], v[32:35]
	v_mfma_f32_16x16x32_bf16 v[20:23], v[176:179], v[208:211], v[20:23]
	v_mfma_f32_16x16x32_bf16 v[16:19], v[184:187], v[208:211], v[16:19]
	v_mfma_f32_16x16x32_bf16 v[4:7], v[176:179], v[216:219], v[4:7]
	v_mfma_f32_16x16x32_bf16 v[0:3], v[184:187], v[216:219], v[0:3]
	s_setprio 0
	s_barrier
	s_add_u32 s6, s6, 0x100
	s_addc_u32 s7, s7, 0
	s_add_u32 s12, s12, 0x100
	s_addc_u32 s13, s13, 0
	s_cmp_ge_i32 s1, s78
	s_mov_b32 s0, s1
	s_cbranch_scc0 .LBB0_1787

; #define PG8_STAGE(bufoff, gbase, voff) do { _Pragma("unroll") for (int _i = 0; _i < 2; ++_i) \
;         __builtin_amdgcn_global_load_lds((const unsigned*)((const char*)(gbase) + (voff)[_i]), (PG8_LAS unsigned*)(lds + (bufoff) + ldsw + _i * 8192), 16, 0, 0); } while (0)
; #define PG8_LDA(dst, b, h) do { _Pragma("unroll") for (int m = 0; m < 4; ++m) _Pragma("unroll") for (int k = 0; k < 2; ++k) dst[m][k] = *(const PG8_LAS bf16x8*)(lds + PG8_SA(b, h) + aoff + m * 2048 + k * 1024); } while (0)
; #define PG8_LDB(dst, b, h) do { _Pragma("unroll") for (int n = 0; n < 2; ++n) _Pragma("unroll") for (int k = 0; k < 2; ++k) dst[n][k] = *(const PG8_LAS bf16x8*)(lds + PG8_SB(b, h) + boff + n * 2048 + k * 1024); } while (0)
; #define PG8_MMA(ai, bj, At, Bt) do { __builtin_amdgcn_s_setprio(1); _Pragma("unroll") for (int m = 0; m < 4; ++m) _Pragma("unroll") for (int n = 0; n < 2; ++n) _Pragma("unroll") for (int k = 0; k < 2; ++k) \
;         acc[ai][bj][m][n] = __builtin_amdgcn_mfma_f32_16x16x32_bf16(Bt[n][k], At[m][k], acc[ai][bj][m][n], 0, 0, 0); __builtin_amdgcn_s_setprio(0); } while (0)
; #define PG8_WAIT_V(n) asm volatile("s_waitcnt vmcnt(" #n ")" ::: "memory")
; #define PG8_WAIT_L(n) asm volatile("s_waitcnt lgkmcnt(" #n ")" ::: "memory")
; #define PG8_BAR __builtin_amdgcn_s_barrier()
; template <class Epi, class Sched, bool ALIGN_EPI = false, bool SP2 = false>
; __device__ __forceinline__ void gemm_phase(PG8_LAS unsigned char* lds, const Gemm g, const Sched& S, const Epi& E, int wv) {
;     ...
;             const char* a1 = cA + (size_t)(t + 1) * kstep;
;             const char* a2 = last ? nA : cA + (size_t)(t + 2) * kstep; const char* b2 = last ? nB : cB + (size_t)(t + 2) * kstep;
;             const char* a3 = a2 + kstep; const char* b3 = b2 + kstep;
;             if (last && has_next) S.a_ready(nxt);
;             if constexpr (SP2) {
;             PG8_LDB(B0, 0, 0); PG8_LDB(B1, 0, 1); PG8_SCHED; PG8_LDA(At, 0, 0); PG8_STAGE(PG8_SA(1, 1), a1 + hstepA, voffA);
;             PG8_WAIT_V(8); PG8_WAIT_L(0); PG8_BAR; PG8_MMA(0, 0, At, B0); PG8_MMA(0, 1, At, B1); PG8_BAR; PG8_SCHED;
;             PG8_LDA(At, 0, 1); PG8_STAGE(PG8_SB(0, 0), b2, voffB); PG8_STAGE(PG8_SB(0, 1), b2 + hstepB, voffB); PG8_STAGE(PG8_SA(0, 0), a2, voffA);
;             PG8_WAIT_V(8); PG8_WAIT_L(0); PG8_BAR; PG8_MMA(1, 0, At, B0); PG8_MMA(1, 1, At, B1); PG8_BAR; PG8_SCHED;
.LBB0_1874:
	ds_read_b128 v[128:131], v202
	ds_read_b128 v[132:135], v202 offset:1024
	ds_read_b128 v[136:139], v202 offset:2048
	ds_read_b128 v[140:143], v202 offset:3072
	ds_read_b128 v[144:147], v203
	ds_read_b128 v[148:151], v203 offset:1024
	ds_read_b128 v[178:181], v203 offset:2048
	ds_read_b128 v[182:185], v203 offset:3072
	s_add_i32 s1, s0, 2
	s_add_u32 s2, s8, 0x80
	s_addc_u32 s3, s9, 0
	s_cmp_eq_u32 s78, s0
	s_cselect_b32 s63, s43, s3
	s_cselect_b32 s62, s42, s2
	s_cselect_b32 s3, s61, s65
	s_cselect_b32 s2, s60, s64
	v_lshl_add_u64 v[196:197], s[8:9], 0, v[168:169]
	s_add_i32 m0, s71, 0xc000
	ds_read_b128 v[186:189], v204
	ds_read_b128 v[190:193], v204 offset:1024
	ds_read_b128 v[206:209], v204 offset:2048
	ds_read_b128 v[210:213], v204 offset:3072
	ds_read_b128 v[214:217], v204 offset:4096
	ds_read_b128 v[218:221], v204 offset:5120
	ds_read_b128 v[222:225], v204 offset:6144
	ds_read_b128 v[226:229], v204 offset:7168
	global_load_lds_dwordx4 v[196:197], off
	v_lshl_add_u64 v[196:197], s[8:9], 0, v[170:171]
	s_add_i32 m0, s71, 0xe000
	s_nop 0
	global_load_lds_dwordx4 v[196:197], off
	s_waitcnt vmcnt(8)
	s_waitcnt lgkmcnt(0)
	s_barrier
	s_setprio 1
	v_mfma_f32_16x16x32_bf16 v[56:59], v[128:131], v[186:189], v[56:59]
	v_mfma_f32_16x16x32_bf16 v[60:63], v[136:139], v[186:189], v[60:63]
	v_mfma_f32_16x16x32_bf16 v[52:55], v[128:131], v[206:209], v[52:55]
	v_mfma_f32_16x16x32_bf16 v[48:51], v[136:139], v[206:209], v[48:51]
	v_mfma_f32_16x16x32_bf16 v[44:47], v[128:131], v[214:217], v[44:47]
	v_mfma_f32_16x16x32_bf16 v[40:43], v[136:139], v[214:217], v[40:43]
	v_mfma_f32_16x16x32_bf16 v[36:39], v[128:131], v[222:225], v[36:39]
	v_mfma_f32_16x16x32_bf16 v[32:35], v[136:139], v[222:225], v[32:35]
	v_mfma_f32_16x16x32_bf16 v[56:59], v[132:135], v[190:193], v[56:59]
	v_mfma_f32_16x16x32_bf16 v[60:63], v[140:143], v[190:193], v[60:63]
	v_mfma_f32_16x16x32_bf16 v[52:55], v[132:135], v[210:213], v[52:55]
	v_mfma_f32_16x16x32_bf16 v[48:51], v[140:143], v[210:213], v[48:51]
	v_mfma_f32_16x16x32_bf16 v[44:47], v[132:135], v[218:221], v[44:47]
	v_mfma_f32_16x16x32_bf16 v[40:43], v[140:143], v[218:221], v[40:43]
	v_mfma_f32_16x16x32_bf16 v[36:39], v[132:135], v[226:229], v[36:39]
	v_mfma_f32_16x16x32_bf16 v[32:35], v[140:143], v[226:229], v[32:35]
	v_mfma_f32_16x16x32_bf16 v[124:127], v[144:147], v[186:189], v[124:127]
	v_mfma_f32_16x16x32_bf16 v[120:123], v[178:181], v[186:189], v[120:123]
	v_mfma_f32_16x16x32_bf16 v[116:119], v[144:147], v[206:209], v[116:119]
	v_mfma_f32_16x16x32_bf16 v[112:115], v[178:181], v[206:209], v[112:115]
	v_mfma_f32_16x16x32_bf16 v[108:111], v[144:147], v[214:217], v[108:111]
	v_mfma_f32_16x16x32_bf16 v[104:107], v[178:181], v[214:217], v[104:107]
	v_mfma_f32_16x16x32_bf16 v[100:103], v[144:147], v[222:225], v[100:103]
	v_mfma_f32_16x16x32_bf16 v[96:99], v[178:181], v[222:225], v[96:99]
	v_mfma_f32_16x16x32_bf16 v[124:127], v[148:151], v[190:193], v[124:127]
	v_mfma_f32_16x16x32_bf16 v[120:123], v[182:185], v[190:193], v[120:123]
	v_mfma_f32_16x16x32_bf16 v[116:119], v[148:151], v[210:213], v[116:119]
	v_mfma_f32_16x16x32_bf16 v[112:115], v[182:185], v[210:213], v[112:115]
	v_mfma_f32_16x16x32_bf16 v[108:111], v[148:151], v[218:221], v[108:111]
	v_mfma_f32_16x16x32_bf16 v[104:107], v[182:185], v[218:221], v[104:107]
	v_mfma_f32_16x16x32_bf16 v[100:103], v[148:151], v[226:229], v[100:103]
	v_mfma_f32_16x16x32_bf16 v[96:99], v[182:185], v[226:229], v[96:99]
	s_setprio 0
	s_barrier
	s_add_i32 s0, s85, s70
	v_lshl_add_u64 v[196:197], s[2:3], 0, v[154:155]
	s_mov_b32 m0, s0
	ds_read_b128 v[186:189], v204 offset:16384
	ds_read_b128 v[190:193], v204 offset:17408
	ds_read_b128 v[206:209], v204 offset:18432
	ds_read_b128 v[210:213], v204 offset:19456
	ds_read_b128 v[214:217], v204 offset:20480
	ds_read_b128 v[218:221], v204 offset:21504
	ds_read_b128 v[222:225], v204 offset:22528
	ds_read_b128 v[226:229], v204 offset:23552
	global_load_lds_dwordx4 v[196:197], off
	s_add_i32 m0, s0, 0x2000
	v_lshl_add_u64 v[230:231], s[2:3], 0, v[158:159]
	s_add_u32 s2, s2, s40
	s_addc_u32 s3, s3, s41
	s_add_i32 s0, s86, s70
	global_load_lds_dwordx4 v[230:231], off
	v_lshl_add_u64 v[232:233], s[2:3], 0, v[154:155]
	s_mov_b32 m0, s0
	v_lshl_add_u64 v[234:235], s[2:3], 0, v[158:159]
	global_load_lds_dwordx4 v[232:233], off
	s_add_i32 m0, s0, 0x2000
	v_lshl_add_u64 v[236:237], s[62:63], 0, v[152:153]
	global_load_lds_dwordx4 v[234:235], off
	s_mov_b32 m0, s71
	v_lshl_add_u64 v[238:239], s[62:63], 0, v[156:157]
	global_load_lds_dwordx4 v[236:237], off
	s_mov_b32 m0, s72
	s_nop 0
	global_load_lds_dwordx4 v[238:239], off
	s_waitcnt vmcnt(8)
	s_waitcnt lgkmcnt(0)
	s_barrier
; #define PG8_STAGE(bufoff, gbase, voff) do { _Pragma("unroll") for (int _i = 0; _i < 2; ++_i) \
;         __builtin_amdgcn_global_load_lds((const unsigned*)((const char*)(gbase) + (voff)[_i]), (PG8_LAS unsigned*)(lds + (bufoff) + ldsw + _i * 8192), 16, 0, 0); } while (0)
; #define PG8_LDA(dst, b, h) do { _Pragma("unroll") for (int m = 0; m < 4; ++m) _Pragma("unroll") for (int k = 0; k < 2; ++k) dst[m][k] = *(const PG8_LAS bf16x8*)(lds + PG8_SA(b, h) + aoff + m * 2048 + k * 1024); } while (0)
; #define PG8_LDB(dst, b, h) do { _Pragma("unroll") for (int n = 0; n < 2; ++n) _Pragma("unroll") for (int k = 0; k < 2; ++k) dst[n][k] = *(const PG8_LAS bf16x8*)(lds + PG8_SB(b, h) + boff + n * 2048 + k * 1024); } while (0)
; #define PG8_MMA(ai, bj, At, Bt) do { __builtin_amdgcn_s_setprio(1); _Pragma("unroll") for (int m = 0; m < 4; ++m) _Pragma("unroll") for (int n = 0; n < 2; ++n) _Pragma("unroll") for (int k = 0; k < 2; ++k) \
;         acc[ai][bj][m][n] = __builtin_amdgcn_mfma_f32_16x16x32_bf16(Bt[n][k], At[m][k], acc[ai][bj][m][n], 0, 0, 0); __builtin_amdgcn_s_setprio(0); } while (0)
; #define PG8_WAIT_V(n) asm volatile("s_waitcnt vmcnt(" #n ")" ::: "memory")
; #define PG8_WAIT_L(n) asm volatile("s_waitcnt lgkmcnt(" #n ")" ::: "memory")
; #define PG8_BAR __builtin_amdgcn_s_barrier()
; #define PG8_SCHED __builtin_amdgcn_sched_barrier(0)
; template <class Epi, class Sched, bool ALIGN_EPI = false, bool SP2 = false>
; __device__ __forceinline__ void gemm_phase(PG8_LAS unsigned char* lds, const Gemm g, const Sched& S, const Epi& E, int wv) {
;     ...
;             PG8_WAIT_V(8); PG8_WAIT_L(0); PG8_BAR; PG8_MMA(1, 0, At, B0); PG8_MMA(1, 1, At, B1); PG8_BAR; PG8_SCHED;
;             PG8_LDB(B0, 1, 0); PG8_LDB(B1, 1, 1); PG8_SCHED; PG8_LDA(At, 1, 0); PG8_STAGE(PG8_SA(0, 1), a2 + hstepA, voffA);
;             PG8_WAIT_V(8); PG8_WAIT_L(0); PG8_BAR; PG8_MMA(0, 0, At, B0); PG8_MMA(0, 1, At, B1); PG8_BAR; PG8_SCHED;
	s_setprio 1
	v_mfma_f32_16x16x32_bf16 v[28:31], v[128:131], v[186:189], v[28:31]
	v_mfma_f32_16x16x32_bf16 v[24:27], v[136:139], v[186:189], v[24:27]
	v_mfma_f32_16x16x32_bf16 v[20:23], v[128:131], v[206:209], v[20:23]
	v_mfma_f32_16x16x32_bf16 v[16:19], v[136:139], v[206:209], v[16:19]
	v_mfma_f32_16x16x32_bf16 v[12:15], v[128:131], v[214:217], v[12:15]
	v_mfma_f32_16x16x32_bf16 v[8:11], v[136:139], v[214:217], v[8:11]
	v_mfma_f32_16x16x32_bf16 v[4:7], v[128:131], v[222:225], v[4:7]
	v_mfma_f32_16x16x32_bf16 v[0:3], v[136:139], v[222:225], v[0:3]
	v_mfma_f32_16x16x32_bf16 v[28:31], v[132:135], v[190:193], v[28:31]
	v_mfma_f32_16x16x32_bf16 v[24:27], v[140:143], v[190:193], v[24:27]
	v_mfma_f32_16x16x32_bf16 v[20:23], v[132:135], v[210:213], v[20:23]
	v_mfma_f32_16x16x32_bf16 v[16:19], v[140:143], v[210:213], v[16:19]
	v_mfma_f32_16x16x32_bf16 v[12:15], v[132:135], v[218:221], v[12:15]
	v_mfma_f32_16x16x32_bf16 v[8:11], v[140:143], v[218:221], v[8:11]
	v_mfma_f32_16x16x32_bf16 v[4:7], v[132:135], v[226:229], v[4:7]
	v_mfma_f32_16x16x32_bf16 v[0:3], v[140:143], v[226:229], v[0:3]
	v_mfma_f32_16x16x32_bf16 v[92:95], v[144:147], v[186:189], v[92:95]
	v_mfma_f32_16x16x32_bf16 v[88:91], v[178:181], v[186:189], v[88:91]
	v_mfma_f32_16x16x32_bf16 v[84:87], v[144:147], v[206:209], v[84:87]
	v_mfma_f32_16x16x32_bf16 v[80:83], v[178:181], v[206:209], v[80:83]
	v_mfma_f32_16x16x32_bf16 v[76:79], v[144:147], v[214:217], v[76:79]
	v_mfma_f32_16x16x32_bf16 v[72:75], v[178:181], v[214:217], v[72:75]
	v_mfma_f32_16x16x32_bf16 v[68:71], v[144:147], v[222:225], v[68:71]
	v_mfma_f32_16x16x32_bf16 v[64:67], v[178:181], v[222:225], v[64:67]
	v_mfma_f32_16x16x32_bf16 v[92:95], v[148:151], v[190:193], v[92:95]
	v_mfma_f32_16x16x32_bf16 v[88:91], v[182:185], v[190:193], v[88:91]
	v_mfma_f32_16x16x32_bf16 v[84:87], v[148:151], v[210:213], v[84:87]
	v_mfma_f32_16x16x32_bf16 v[80:83], v[182:185], v[210:213], v[80:83]
	v_mfma_f32_16x16x32_bf16 v[76:79], v[148:151], v[218:221], v[76:79]
	v_mfma_f32_16x16x32_bf16 v[72:75], v[182:185], v[218:221], v[72:75]
	v_mfma_f32_16x16x32_bf16 v[68:71], v[148:151], v[226:229], v[68:71]
	v_mfma_f32_16x16x32_bf16 v[64:67], v[182:185], v[226:229], v[64:67]
	s_setprio 0
	s_barrier
	s_add_i32 s0, 0, 0x18000
	s_add_i32 s94, 0, 0x1c000
	v_add_u32_e32 v140, s0, v195
	v_add_u32_e32 v177, s94, v195
	ds_read_b128 v[128:131], v140
	ds_read_b128 v[132:135], v140 offset:1024
	ds_read_b128 v[136:139], v140 offset:2048
	ds_read_b128 v[140:143], v140 offset:3072
	ds_read_b128 v[144:147], v177
	ds_read_b128 v[148:151], v177 offset:1024
	ds_read_b128 v[178:181], v177 offset:2048
	ds_read_b128 v[182:185], v177 offset:3072
	s_add_u32 s2, s62, s38
	s_addc_u32 s3, s63, s39
	s_mov_b32 m0, s73
	v_lshl_add_u64 v[240:241], s[2:3], 0, v[152:153]
	ds_read_b128 v[186:189], v204 offset:32768
	ds_read_b128 v[190:193], v204 offset:33792
	ds_read_b128 v[206:209], v204 offset:34816
	ds_read_b128 v[210:213], v204 offset:35840
	ds_read_b128 v[214:217], v204 offset:36864
	ds_read_b128 v[218:221], v204 offset:37888
	ds_read_b128 v[222:225], v204 offset:38912
	ds_read_b128 v[226:229], v204 offset:39936
	global_load_lds_dwordx4 v[240:241], off
	v_lshl_add_u64 v[240:241], s[2:3], 0, v[156:157]
	s_mov_b32 m0, s74
	s_nop 0
	global_load_lds_dwordx4 v[240:241], off
	s_waitcnt vmcnt(8)
	s_waitcnt lgkmcnt(0)
	s_barrier
	s_setprio 1
	v_mfma_f32_16x16x32_bf16 v[56:59], v[128:131], v[186:189], v[56:59]
	v_mfma_f32_16x16x32_bf16 v[60:63], v[136:139], v[186:189], v[60:63]
	v_mfma_f32_16x16x32_bf16 v[52:55], v[128:131], v[206:209], v[52:55]
	v_mfma_f32_16x16x32_bf16 v[48:51], v[136:139], v[206:209], v[48:51]
	v_mfma_f32_16x16x32_bf16 v[44:47], v[128:131], v[214:217], v[44:47]
	v_mfma_f32_16x16x32_bf16 v[40:43], v[136:139], v[214:217], v[40:43]
	v_mfma_f32_16x16x32_bf16 v[36:39], v[128:131], v[222:225], v[36:39]
	v_mfma_f32_16x16x32_bf16 v[32:35], v[136:139], v[222:225], v[32:35]
	v_mfma_f32_16x16x32_bf16 v[56:59], v[132:135], v[190:193], v[56:59]
	v_mfma_f32_16x16x32_bf16 v[60:63], v[140:143], v[190:193], v[60:63]
	v_mfma_f32_16x16x32_bf16 v[52:55], v[132:135], v[210:213], v[52:55]
	v_mfma_f32_16x16x32_bf16 v[48:51], v[140:143], v[210:213], v[48:51]
	v_mfma_f32_16x16x32_bf16 v[44:47], v[132:135], v[218:221], v[44:47]
	v_mfma_f32_16x16x32_bf16 v[40:43], v[140:143], v[218:221], v[40:43]
	v_mfma_f32_16x16x32_bf16 v[36:39], v[132:135], v[226:229], v[36:39]
	v_mfma_f32_16x16x32_bf16 v[32:35], v[140:143], v[226:229], v[32:35]
	v_mfma_f32_16x16x32_bf16 v[124:127], v[144:147], v[186:189], v[124:127]
	v_mfma_f32_16x16x32_bf16 v[120:123], v[178:181], v[186:189], v[120:123]
	v_mfma_f32_16x16x32_bf16 v[116:119], v[144:147], v[206:209], v[116:119]
	v_mfma_f32_16x16x32_bf16 v[112:115], v[178:181], v[206:209], v[112:115]
	v_mfma_f32_16x16x32_bf16 v[108:111], v[144:147], v[214:217], v[108:111]
	v_mfma_f32_16x16x32_bf16 v[104:107], v[178:181], v[214:217], v[104:107]
	v_mfma_f32_16x16x32_bf16 v[100:103], v[144:147], v[222:225], v[100:103]
	v_mfma_f32_16x16x32_bf16 v[96:99], v[178:181], v[222:225], v[96:99]
	v_mfma_f32_16x16x32_bf16 v[124:127], v[148:151], v[190:193], v[124:127]
	v_mfma_f32_16x16x32_bf16 v[120:123], v[182:185], v[190:193], v[120:123]
	v_mfma_f32_16x16x32_bf16 v[116:119], v[148:151], v[210:213], v[116:119]
	v_mfma_f32_16x16x32_bf16 v[112:115], v[182:185], v[210:213], v[112:115]
	v_mfma_f32_16x16x32_bf16 v[108:111], v[148:151], v[218:221], v[108:111]
	v_mfma_f32_16x16x32_bf16 v[104:107], v[182:185], v[218:221], v[104:107]
	v_mfma_f32_16x16x32_bf16 v[100:103], v[148:151], v[226:229], v[100:103]
	v_mfma_f32_16x16x32_bf16 v[96:99], v[182:185], v[226:229], v[96:99]
	s_setprio 0
	s_barrier
; #define PG8_STAGE(bufoff, gbase, voff) do { _Pragma("unroll") for (int _i = 0; _i < 2; ++_i) \
;         __builtin_amdgcn_global_load_lds((const unsigned*)((const char*)(gbase) + (voff)[_i]), (PG8_LAS unsigned*)(lds + (bufoff) + ldsw + _i * 8192), 16, 0, 0); } while (0)
; #define PG8_LDA(dst, b, h) do { _Pragma("unroll") for (int m = 0; m < 4; ++m) _Pragma("unroll") for (int k = 0; k < 2; ++k) dst[m][k] = *(const PG8_LAS bf16x8*)(lds + PG8_SA(b, h) + aoff + m * 2048 + k * 1024); } while (0)
; #define PG8_MMA(ai, bj, At, Bt) do { __builtin_amdgcn_s_setprio(1); _Pragma("unroll") for (int m = 0; m < 4; ++m) _Pragma("unroll") for (int n = 0; n < 2; ++n) _Pragma("unroll") for (int k = 0; k < 2; ++k) \
;         acc[ai][bj][m][n] = __builtin_amdgcn_mfma_f32_16x16x32_bf16(Bt[n][k], At[m][k], acc[ai][bj][m][n], 0, 0, 0); __builtin_amdgcn_s_setprio(0); } while (0)
; #define PG8_WAIT_V(n) asm volatile("s_waitcnt vmcnt(" #n ")" ::: "memory")
; #define PG8_WAIT_L(n) asm volatile("s_waitcnt lgkmcnt(" #n ")" ::: "memory")
; #define PG8_BAR __builtin_amdgcn_s_barrier()
; #define PG8_SCHED __builtin_amdgcn_sched_barrier(0)
; template <class Epi, class Sched, bool ALIGN_EPI = false, bool SP2 = false>
; __device__ __forceinline__ void gemm_phase(PG8_LAS unsigned char* lds, const Gemm g, const Sched& S, const Epi& E, int wv) {
;     ...
;         for (int t = 0; t < nt; t += 2) {
;     ...
;             PG8_LDA(At, 1, 1); PG8_STAGE(PG8_SB(1, 0), b3, voffB); PG8_STAGE(PG8_SB(1, 1), b3 + hstepB, voffB); PG8_STAGE(PG8_SA(1, 0), a3, voffA);
;             PG8_WAIT_V(8); PG8_WAIT_L(0); PG8_BAR; PG8_MMA(1, 0, At, B0); PG8_MMA(1, 1, At, B1); PG8_BAR; PG8_SCHED;
	s_add_i32 s0, s0, s70
	v_lshl_add_u64 v[196:197], v[196:197], 0, s[54:55]
	s_mov_b32 m0, s0
	ds_read_b128 v[186:189], v204 offset:49152
	ds_read_b128 v[190:193], v204 offset:50176
	ds_read_b128 v[206:209], v204 offset:51200
	ds_read_b128 v[210:213], v204 offset:52224
	ds_read_b128 v[214:217], v204 offset:53248
	ds_read_b128 v[218:221], v204 offset:54272
	ds_read_b128 v[222:225], v204 offset:55296
	ds_read_b128 v[226:229], v204 offset:56320
	global_load_lds_dwordx4 v[196:197], off
	v_lshl_add_u64 v[196:197], v[230:231], 0, s[54:55]
	s_add_i32 m0, s0, 0x2000
	s_add_i32 s0, s94, s70
	global_load_lds_dwordx4 v[196:197], off
	v_lshl_add_u64 v[196:197], v[232:233], 0, s[54:55]
	s_mov_b32 m0, s0
	s_nop 0
	global_load_lds_dwordx4 v[196:197], off
	v_lshl_add_u64 v[196:197], v[234:235], 0, s[54:55]
	s_add_i32 m0, s0, 0x2000
	s_nop 0
	global_load_lds_dwordx4 v[196:197], off
	v_lshl_add_u64 v[196:197], v[236:237], 0, s[54:55]
	s_mov_b32 m0, s75
	s_nop 0
	global_load_lds_dwordx4 v[196:197], off
	v_lshl_add_u64 v[196:197], v[238:239], 0, s[54:55]
	s_mov_b32 m0, s76
	s_nop 0
	global_load_lds_dwordx4 v[196:197], off
	s_waitcnt vmcnt(8)
	s_waitcnt lgkmcnt(0)
	s_barrier
	s_setprio 1
	v_mfma_f32_16x16x32_bf16 v[28:31], v[128:131], v[186:189], v[28:31]
	v_mfma_f32_16x16x32_bf16 v[24:27], v[136:139], v[186:189], v[24:27]
	v_mfma_f32_16x16x32_bf16 v[20:23], v[128:131], v[206:209], v[20:23]
	v_mfma_f32_16x16x32_bf16 v[16:19], v[136:139], v[206:209], v[16:19]
	v_mfma_f32_16x16x32_bf16 v[12:15], v[128:131], v[214:217], v[12:15]
	v_mfma_f32_16x16x32_bf16 v[8:11], v[136:139], v[214:217], v[8:11]
	v_mfma_f32_16x16x32_bf16 v[4:7], v[128:131], v[222:225], v[4:7]
	v_mfma_f32_16x16x32_bf16 v[0:3], v[136:139], v[222:225], v[0:3]
	v_mfma_f32_16x16x32_bf16 v[28:31], v[132:135], v[190:193], v[28:31]
	v_mfma_f32_16x16x32_bf16 v[24:27], v[140:143], v[190:193], v[24:27]
	v_mfma_f32_16x16x32_bf16 v[20:23], v[132:135], v[210:213], v[20:23]
	v_mfma_f32_16x16x32_bf16 v[16:19], v[140:143], v[210:213], v[16:19]
	v_mfma_f32_16x16x32_bf16 v[12:15], v[132:135], v[218:221], v[12:15]
	v_mfma_f32_16x16x32_bf16 v[8:11], v[140:143], v[218:221], v[8:11]
	v_mfma_f32_16x16x32_bf16 v[4:7], v[132:135], v[226:229], v[4:7]
	v_mfma_f32_16x16x32_bf16 v[0:3], v[140:143], v[226:229], v[0:3]
	v_mfma_f32_16x16x32_bf16 v[92:95], v[144:147], v[186:189], v[92:95]
	v_mfma_f32_16x16x32_bf16 v[88:91], v[178:181], v[186:189], v[88:91]
	v_mfma_f32_16x16x32_bf16 v[84:87], v[144:147], v[206:209], v[84:87]
	v_mfma_f32_16x16x32_bf16 v[80:83], v[178:181], v[206:209], v[80:83]
	v_mfma_f32_16x16x32_bf16 v[76:79], v[144:147], v[214:217], v[76:79]
	v_mfma_f32_16x16x32_bf16 v[72:75], v[178:181], v[214:217], v[72:75]
	v_mfma_f32_16x16x32_bf16 v[68:71], v[144:147], v[222:225], v[68:71]
	v_mfma_f32_16x16x32_bf16 v[64:67], v[178:181], v[222:225], v[64:67]
	v_mfma_f32_16x16x32_bf16 v[92:95], v[148:151], v[190:193], v[92:95]
	v_mfma_f32_16x16x32_bf16 v[88:91], v[182:185], v[190:193], v[88:91]
	v_mfma_f32_16x16x32_bf16 v[84:87], v[148:151], v[210:213], v[84:87]
	v_mfma_f32_16x16x32_bf16 v[80:83], v[182:185], v[210:213], v[80:83]
	v_mfma_f32_16x16x32_bf16 v[76:79], v[148:151], v[218:221], v[76:79]
	v_mfma_f32_16x16x32_bf16 v[72:75], v[182:185], v[218:221], v[72:75]
	v_mfma_f32_16x16x32_bf16 v[68:71], v[148:151], v[226:229], v[68:71]
	v_mfma_f32_16x16x32_bf16 v[64:67], v[182:185], v[226:229], v[64:67]
	s_setprio 0
	s_barrier
	s_add_u32 s8, s8, 0x100
	s_addc_u32 s9, s9, 0
	s_add_u32 s64, s64, 0x100
	s_addc_u32 s65, s65, 0
	s_cmp_ge_i32 s1, s77
	s_mov_b32 s0, s1
	s_cbranch_scc0 .LBB0_1874

; #define PG8_STAGE(bufoff, gbase, voff) do { _Pragma("unroll") for (int _i = 0; _i < 2; ++_i) \
;         __builtin_amdgcn_global_load_lds((const unsigned*)((const char*)(gbase) + (voff)[_i]), (PG8_LAS unsigned*)(lds + (bufoff) + ldsw + _i * 8192), 16, 0, 0); } while (0)
; #define PG8_LDA(dst, b, h) do { _Pragma("unroll") for (int m = 0; m < 4; ++m) _Pragma("unroll") for (int k = 0; k < 2; ++k) dst[m][k] = *(const PG8_LAS bf16x8*)(lds + PG8_SA(b, h) + aoff + m * 2048 + k * 1024); } while (0)
; #define PG8_LDB(dst, b, h) do { _Pragma("unroll") for (int n = 0; n < 2; ++n) _Pragma("unroll") for (int k = 0; k < 2; ++k) dst[n][k] = *(const PG8_LAS bf16x8*)(lds + PG8_SB(b, h) + boff + n * 2048 + k * 1024); } while (0)
; #define PG8_MMA(ai, bj, At, Bt) do { __builtin_amdgcn_s_setprio(1); _Pragma("unroll") for (int m = 0; m < 4; ++m) _Pragma("unroll") for (int n = 0; n < 2; ++n) _Pragma("unroll") for (int k = 0; k < 2; ++k) \
;         acc[ai][bj][m][n] = __builtin_amdgcn_mfma_f32_16x16x32_bf16(Bt[n][k], At[m][k], acc[ai][bj][m][n], 0, 0, 0); __builtin_amdgcn_s_setprio(0); } while (0)
; #define PG8_WAIT_V(n) asm volatile("s_waitcnt vmcnt(" #n ")" ::: "memory")
; #define PG8_WAIT_L(n) asm volatile("s_waitcnt lgkmcnt(" #n ")" ::: "memory")
; #define PG8_BAR __builtin_amdgcn_s_barrier()
; template <class Epi, class Sched, bool ALIGN_EPI = false, bool SP2 = false>
; __device__ __forceinline__ void gemm_phase(PG8_LAS unsigned char* lds, const Gemm g, const Sched& S, const Epi& E, int wv) {
;     ...
;             const char* a1 = cA + (size_t)(t + 1) * kstep;
;             const char* a2 = last ? nA : cA + (size_t)(t + 2) * kstep; const char* b2 = last ? nB : cB + (size_t)(t + 2) * kstep;
;             const char* a3 = a2 + kstep; const char* b3 = b2 + kstep;
;             if (last && has_next) S.a_ready(nxt);
;             if constexpr (SP2) {
;             PG8_LDB(B0, 0, 0); PG8_LDB(B1, 0, 1); PG8_SCHED; PG8_LDA(At, 0, 0); PG8_STAGE(PG8_SA(1, 1), a1 + hstepA, voffA);
;             PG8_WAIT_V(8); PG8_WAIT_L(0); PG8_BAR; PG8_MMA(0, 0, At, B0); PG8_MMA(0, 1, At, B1); PG8_BAR; PG8_SCHED;
;             PG8_LDA(At, 0, 1); PG8_STAGE(PG8_SB(0, 0), b2, voffB); PG8_STAGE(PG8_SB(0, 1), b2 + hstepB, voffB); PG8_STAGE(PG8_SA(0, 0), a2, voffA);
;             PG8_WAIT_V(8); PG8_WAIT_L(0); PG8_BAR; PG8_MMA(1, 0, At, B0); PG8_MMA(1, 1, At, B1); PG8_BAR; PG8_SCHED;
.LBB0_2016:
	ds_read_b128 v[144:147], v153
	ds_read_b128 v[156:159], v153 offset:1024
	ds_read_b128 v[160:163], v153 offset:2048
	ds_read_b128 v[164:167], v153 offset:3072
	ds_read_b128 v[168:171], v154
	ds_read_b128 v[172:175], v154 offset:1024
	ds_read_b128 v[176:179], v154 offset:2048
	ds_read_b128 v[180:183], v154 offset:3072
	s_add_u32 s0, s38, 0xfffc0080
	s_addc_u32 s1, s39, -1
	s_cmp_eq_u32 s62, 12
	s_cselect_b32 s43, s23, s1
	s_cselect_b32 s42, s29, s0
	s_cselect_b32 s41, s21, s59
	s_cselect_b32 s40, s57, s58
	s_add_i32 m0, s37, 0xc000
	ds_read_b128 v[184:187], v155
	ds_read_b128 v[188:191], v155 offset:1024
	ds_read_b128 v[192:195], v155 offset:2048
	ds_read_b128 v[196:199], v155 offset:3072
	ds_read_b128 v[200:203], v155 offset:4096
	ds_read_b128 v[204:207], v155 offset:5120
	ds_read_b128 v[208:211], v155 offset:6144
	ds_read_b128 v[212:215], v155 offset:7168
	global_load_lds_dwordx4 v136, s[38:39]
	s_add_i32 m0, s37, 0xe000
	s_nop 0
	global_load_lds_dwordx4 v138, s[38:39]
	s_waitcnt vmcnt(8)
	s_waitcnt lgkmcnt(0)
	s_barrier
	s_setprio 1
	v_mfma_f32_16x16x32_bf16 v[124:127], v[144:147], v[184:187], v[124:127]
	v_mfma_f32_16x16x32_bf16 v[120:123], v[160:163], v[184:187], v[120:123]
	v_mfma_f32_16x16x32_bf16 v[108:111], v[144:147], v[192:195], v[108:111]
	v_mfma_f32_16x16x32_bf16 v[104:107], v[160:163], v[192:195], v[104:107]
	v_mfma_f32_16x16x32_bf16 v[92:95], v[144:147], v[200:203], v[92:95]
	v_mfma_f32_16x16x32_bf16 v[88:91], v[160:163], v[200:203], v[88:91]
	v_mfma_f32_16x16x32_bf16 v[76:79], v[144:147], v[208:211], v[76:79]
	v_mfma_f32_16x16x32_bf16 v[72:75], v[160:163], v[208:211], v[72:75]
	v_mfma_f32_16x16x32_bf16 v[124:127], v[156:159], v[188:191], v[124:127]
	v_mfma_f32_16x16x32_bf16 v[120:123], v[164:167], v[188:191], v[120:123]
	v_mfma_f32_16x16x32_bf16 v[108:111], v[156:159], v[196:199], v[108:111]
	v_mfma_f32_16x16x32_bf16 v[104:107], v[164:167], v[196:199], v[104:107]
	v_mfma_f32_16x16x32_bf16 v[92:95], v[156:159], v[204:207], v[92:95]
	v_mfma_f32_16x16x32_bf16 v[88:91], v[164:167], v[204:207], v[88:91]
	v_mfma_f32_16x16x32_bf16 v[76:79], v[156:159], v[212:215], v[76:79]
	v_mfma_f32_16x16x32_bf16 v[72:75], v[164:167], v[212:215], v[72:75]
	v_mfma_f32_16x16x32_bf16 v[116:119], v[168:171], v[184:187], v[116:119]
	v_mfma_f32_16x16x32_bf16 v[112:115], v[176:179], v[184:187], v[112:115]
	v_mfma_f32_16x16x32_bf16 v[100:103], v[168:171], v[192:195], v[100:103]
	v_mfma_f32_16x16x32_bf16 v[96:99], v[176:179], v[192:195], v[96:99]
	v_mfma_f32_16x16x32_bf16 v[84:87], v[168:171], v[200:203], v[84:87]
	v_mfma_f32_16x16x32_bf16 v[80:83], v[176:179], v[200:203], v[80:83]
	v_mfma_f32_16x16x32_bf16 v[68:71], v[168:171], v[208:211], v[68:71]
	v_mfma_f32_16x16x32_bf16 v[64:67], v[176:179], v[208:211], v[64:67]
	v_mfma_f32_16x16x32_bf16 v[116:119], v[172:175], v[188:191], v[116:119]
	v_mfma_f32_16x16x32_bf16 v[112:115], v[180:183], v[188:191], v[112:115]
	v_mfma_f32_16x16x32_bf16 v[100:103], v[172:175], v[196:199], v[100:103]
	v_mfma_f32_16x16x32_bf16 v[96:99], v[180:183], v[196:199], v[96:99]
	v_mfma_f32_16x16x32_bf16 v[84:87], v[172:175], v[204:207], v[84:87]
	v_mfma_f32_16x16x32_bf16 v[80:83], v[180:183], v[204:207], v[80:83]
	v_mfma_f32_16x16x32_bf16 v[68:71], v[172:175], v[212:215], v[68:71]
	v_mfma_f32_16x16x32_bf16 v[64:67], v[180:183], v[212:215], v[64:67]
	s_setprio 0
	s_barrier
	s_add_i32 s0, s55, s46
	s_mov_b32 m0, s0
	ds_read_b128 v[184:187], v155 offset:16384
	ds_read_b128 v[188:191], v155 offset:17408
	ds_read_b128 v[192:195], v155 offset:18432
	ds_read_b128 v[196:199], v155 offset:19456
	ds_read_b128 v[200:203], v155 offset:20480
	ds_read_b128 v[204:207], v155 offset:21504
	ds_read_b128 v[208:211], v155 offset:22528
	ds_read_b128 v[212:215], v155 offset:23552
	global_load_lds_dwordx4 v130, s[40:41]
	s_add_i32 m0, s0, 0x2000
	s_add_u32 s0, s40, 0x40000
	s_addc_u32 s1, s41, 0
	s_add_i32 s63, s56, s46
	global_load_lds_dwordx4 v134, s[40:41]
	s_mov_b32 m0, s63
	s_nop 0
	global_load_lds_dwordx4 v130, s[0:1]
	s_add_i32 m0, s63, 0x2000
	s_nop 0
	global_load_lds_dwordx4 v134, s[0:1]
	s_mov_b32 m0, s37
	s_nop 0
	global_load_lds_dwordx4 v128, s[42:43]
	s_mov_b32 m0, s47
	s_nop 0
	global_load_lds_dwordx4 v132, s[42:43]
	s_waitcnt vmcnt(8)
	s_waitcnt lgkmcnt(0)
	s_barrier
	s_setprio 1
	v_mfma_f32_16x16x32_bf16 v[60:63], v[144:147], v[184:187], v[60:63]
	v_mfma_f32_16x16x32_bf16 v[56:59], v[160:163], v[184:187], v[56:59]
	v_mfma_f32_16x16x32_bf16 v[44:47], v[144:147], v[192:195], v[44:47]
	v_mfma_f32_16x16x32_bf16 v[40:43], v[160:163], v[192:195], v[40:43]
	v_mfma_f32_16x16x32_bf16 v[28:31], v[144:147], v[200:203], v[28:31]
	v_mfma_f32_16x16x32_bf16 v[24:27], v[160:163], v[200:203], v[24:27]
	v_mfma_f32_16x16x32_bf16 v[12:15], v[144:147], v[208:211], v[12:15]
	v_mfma_f32_16x16x32_bf16 v[8:11], v[160:163], v[208:211], v[8:11]
	v_mfma_f32_16x16x32_bf16 v[60:63], v[156:159], v[188:191], v[60:63]
	v_mfma_f32_16x16x32_bf16 v[56:59], v[164:167], v[188:191], v[56:59]
	v_mfma_f32_16x16x32_bf16 v[44:47], v[156:159], v[196:199], v[44:47]
	v_mfma_f32_16x16x32_bf16 v[40:43], v[164:167], v[196:199], v[40:43]
	v_mfma_f32_16x16x32_bf16 v[28:31], v[156:159], v[204:207], v[28:31]
	v_mfma_f32_16x16x32_bf16 v[24:27], v[164:167], v[204:207], v[24:27]
	v_mfma_f32_16x16x32_bf16 v[12:15], v[156:159], v[212:215], v[12:15]
	v_mfma_f32_16x16x32_bf16 v[8:11], v[164:167], v[212:215], v[8:11]
	v_mfma_f32_16x16x32_bf16 v[52:55], v[168:171], v[184:187], v[52:55]
	v_mfma_f32_16x16x32_bf16 v[48:51], v[176:179], v[184:187], v[48:51]
	v_mfma_f32_16x16x32_bf16 v[36:39], v[168:171], v[192:195], v[36:39]
	v_mfma_f32_16x16x32_bf16 v[32:35], v[176:179], v[192:195], v[32:35]
	v_mfma_f32_16x16x32_bf16 v[20:23], v[168:171], v[200:203], v[20:23]
	v_mfma_f32_16x16x32_bf16 v[16:19], v[176:179], v[200:203], v[16:19]
	v_mfma_f32_16x16x32_bf16 v[4:7], v[168:171], v[208:211], v[4:7]
	v_mfma_f32_16x16x32_bf16 v[0:3], v[176:179], v[208:211], v[0:3]
	v_mfma_f32_16x16x32_bf16 v[52:55], v[172:175], v[188:191], v[52:55]
	v_mfma_f32_16x16x32_bf16 v[48:51], v[180:183], v[188:191], v[48:51]
	v_mfma_f32_16x16x32_bf16 v[36:39], v[172:175], v[196:199], v[36:39]
	v_mfma_f32_16x16x32_bf16 v[32:35], v[180:183], v[196:199], v[32:35]
	v_mfma_f32_16x16x32_bf16 v[20:23], v[172:175], v[204:207], v[20:23]
	v_mfma_f32_16x16x32_bf16 v[16:19], v[180:183], v[204:207], v[16:19]
	v_mfma_f32_16x16x32_bf16 v[4:7], v[172:175], v[212:215], v[4:7]
	v_mfma_f32_16x16x32_bf16 v[0:3], v[180:183], v[212:215], v[0:3]
	s_setprio 0
	s_barrier
; #define PG8_STAGE(bufoff, gbase, voff) do { _Pragma("unroll") for (int _i = 0; _i < 2; ++_i) \
;         __builtin_amdgcn_global_load_lds((const unsigned*)((const char*)(gbase) + (voff)[_i]), (PG8_LAS unsigned*)(lds + (bufoff) + ldsw + _i * 8192), 16, 0, 0); } while (0)
; #define PG8_LDA(dst, b, h) do { _Pragma("unroll") for (int m = 0; m < 4; ++m) _Pragma("unroll") for (int k = 0; k < 2; ++k) dst[m][k] = *(const PG8_LAS bf16x8*)(lds + PG8_SA(b, h) + aoff + m * 2048 + k * 1024); } while (0)
; #define PG8_LDB(dst, b, h) do { _Pragma("unroll") for (int n = 0; n < 2; ++n) _Pragma("unroll") for (int k = 0; k < 2; ++k) dst[n][k] = *(const PG8_LAS bf16x8*)(lds + PG8_SB(b, h) + boff + n * 2048 + k * 1024); } while (0)
; #define PG8_MMA(ai, bj, At, Bt) do { __builtin_amdgcn_s_setprio(1); _Pragma("unroll") for (int m = 0; m < 4; ++m) _Pragma("unroll") for (int n = 0; n < 2; ++n) _Pragma("unroll") for (int k = 0; k < 2; ++k) \
;         acc[ai][bj][m][n] = __builtin_amdgcn_mfma_f32_16x16x32_bf16(Bt[n][k], At[m][k], acc[ai][bj][m][n], 0, 0, 0); __builtin_amdgcn_s_setprio(0); } while (0)
; #define PG8_WAIT_V(n) asm volatile("s_waitcnt vmcnt(" #n ")" ::: "memory")
; #define PG8_WAIT_L(n) asm volatile("s_waitcnt lgkmcnt(" #n ")" ::: "memory")
; #define PG8_BAR __builtin_amdgcn_s_barrier()
; #define PG8_SCHED __builtin_amdgcn_sched_barrier(0)
; template <class Epi, class Sched, bool ALIGN_EPI = false, bool SP2 = false>
; __device__ __forceinline__ void gemm_phase(PG8_LAS unsigned char* lds, const Gemm g, const Sched& S, const Epi& E, int wv) {
;     ...
;             PG8_LDB(B0, 1, 0); PG8_LDB(B1, 1, 1); PG8_SCHED; PG8_LDA(At, 1, 0); PG8_STAGE(PG8_SA(0, 1), a2 + hstepA, voffA);
;             PG8_WAIT_V(8); PG8_WAIT_L(0); PG8_BAR; PG8_MMA(0, 0, At, B0); PG8_MMA(0, 1, At, B1); PG8_BAR; PG8_SCHED;
;             PG8_LDA(At, 1, 1); PG8_STAGE(PG8_SB(1, 0), b3, voffB); PG8_STAGE(PG8_SB(1, 1), b3 + hstepB, voffB); PG8_STAGE(PG8_SA(1, 0), a3, voffA);
;             PG8_WAIT_V(8); PG8_WAIT_L(0); PG8_BAR; PG8_MMA(1, 0, At, B0); PG8_MMA(1, 1, At, B1); PG8_BAR; PG8_SCHED;
	s_add_i32 s63, 0, 0x18000
	s_add_i32 s64, 0, 0x1c000
	v_add_u32_e32 v164, s63, v149
	v_add_u32_e32 v180, s64, v149
	ds_read_b128 v[144:147], v164
	ds_read_b128 v[156:159], v164 offset:1024
	ds_read_b128 v[160:163], v164 offset:2048
	ds_read_b128 v[164:167], v164 offset:3072
	ds_read_b128 v[168:171], v180
	ds_read_b128 v[172:175], v180 offset:1024
	ds_read_b128 v[176:179], v180 offset:2048
	ds_read_b128 v[180:183], v180 offset:3072
	s_add_u32 s0, s42, 0x40000
	s_addc_u32 s1, s43, 0
	s_mov_b32 m0, s48
	ds_read_b128 v[184:187], v155 offset:32768
	ds_read_b128 v[188:191], v155 offset:33792
	ds_read_b128 v[192:195], v155 offset:34816
	ds_read_b128 v[196:199], v155 offset:35840
	ds_read_b128 v[200:203], v155 offset:36864
	ds_read_b128 v[204:207], v155 offset:37888
	ds_read_b128 v[208:211], v155 offset:38912
	ds_read_b128 v[212:215], v155 offset:39936
	global_load_lds_dwordx4 v128, s[0:1]
	s_mov_b32 m0, s49
	s_nop 0
	global_load_lds_dwordx4 v132, s[0:1]
	s_waitcnt vmcnt(8)
	s_waitcnt lgkmcnt(0)
	s_barrier
	s_setprio 1
	v_mfma_f32_16x16x32_bf16 v[124:127], v[144:147], v[184:187], v[124:127]
	v_mfma_f32_16x16x32_bf16 v[120:123], v[160:163], v[184:187], v[120:123]
	v_mfma_f32_16x16x32_bf16 v[108:111], v[144:147], v[192:195], v[108:111]
	v_mfma_f32_16x16x32_bf16 v[104:107], v[160:163], v[192:195], v[104:107]
	v_mfma_f32_16x16x32_bf16 v[92:95], v[144:147], v[200:203], v[92:95]
	v_mfma_f32_16x16x32_bf16 v[88:91], v[160:163], v[200:203], v[88:91]
	v_mfma_f32_16x16x32_bf16 v[76:79], v[144:147], v[208:211], v[76:79]
	v_mfma_f32_16x16x32_bf16 v[72:75], v[160:163], v[208:211], v[72:75]
	v_mfma_f32_16x16x32_bf16 v[124:127], v[156:159], v[188:191], v[124:127]
	v_mfma_f32_16x16x32_bf16 v[120:123], v[164:167], v[188:191], v[120:123]
	v_mfma_f32_16x16x32_bf16 v[108:111], v[156:159], v[196:199], v[108:111]
	v_mfma_f32_16x16x32_bf16 v[104:107], v[164:167], v[196:199], v[104:107]
	v_mfma_f32_16x16x32_bf16 v[92:95], v[156:159], v[204:207], v[92:95]
	v_mfma_f32_16x16x32_bf16 v[88:91], v[164:167], v[204:207], v[88:91]
	v_mfma_f32_16x16x32_bf16 v[76:79], v[156:159], v[212:215], v[76:79]
	v_mfma_f32_16x16x32_bf16 v[72:75], v[164:167], v[212:215], v[72:75]
	v_mfma_f32_16x16x32_bf16 v[116:119], v[168:171], v[184:187], v[116:119]
	v_mfma_f32_16x16x32_bf16 v[112:115], v[176:179], v[184:187], v[112:115]
	v_mfma_f32_16x16x32_bf16 v[100:103], v[168:171], v[192:195], v[100:103]
	v_mfma_f32_16x16x32_bf16 v[96:99], v[176:179], v[192:195], v[96:99]
	v_mfma_f32_16x16x32_bf16 v[84:87], v[168:171], v[200:203], v[84:87]
	v_mfma_f32_16x16x32_bf16 v[80:83], v[176:179], v[200:203], v[80:83]
	v_mfma_f32_16x16x32_bf16 v[68:71], v[168:171], v[208:211], v[68:71]
	v_mfma_f32_16x16x32_bf16 v[64:67], v[176:179], v[208:211], v[64:67]
	v_mfma_f32_16x16x32_bf16 v[116:119], v[172:175], v[188:191], v[116:119]
	v_mfma_f32_16x16x32_bf16 v[112:115], v[180:183], v[188:191], v[112:115]
	v_mfma_f32_16x16x32_bf16 v[100:103], v[172:175], v[196:199], v[100:103]
	v_mfma_f32_16x16x32_bf16 v[96:99], v[180:183], v[196:199], v[96:99]
	v_mfma_f32_16x16x32_bf16 v[84:87], v[172:175], v[204:207], v[84:87]
	v_mfma_f32_16x16x32_bf16 v[80:83], v[180:183], v[204:207], v[80:83]
	v_mfma_f32_16x16x32_bf16 v[68:71], v[172:175], v[212:215], v[68:71]
	v_mfma_f32_16x16x32_bf16 v[64:67], v[180:183], v[212:215], v[64:67]
	s_setprio 0
	s_barrier
	s_add_i32 s0, s63, s46
	s_add_u32 s76, s40, 0x80
	s_addc_u32 s77, s41, 0
	s_mov_b32 m0, s0
	ds_read_b128 v[184:187], v155 offset:49152
	ds_read_b128 v[188:191], v155 offset:50176
	ds_read_b128 v[192:195], v155 offset:51200
	ds_read_b128 v[196:199], v155 offset:52224
	ds_read_b128 v[200:203], v155 offset:53248
	ds_read_b128 v[204:207], v155 offset:54272
	ds_read_b128 v[208:211], v155 offset:55296
	ds_read_b128 v[212:215], v155 offset:56320
	global_load_lds_dwordx4 v130, s[76:77]
	s_add_i32 m0, s0, 0x2000
	s_add_u32 s0, s40, 0x40080
	s_addc_u32 s1, s41, 0
	s_add_i32 s40, s64, s46
	global_load_lds_dwordx4 v134, s[76:77]
	s_mov_b32 m0, s40
	s_nop 0
	global_load_lds_dwordx4 v130, s[0:1]
	s_add_i32 m0, s40, 0x2000
	s_nop 0
	global_load_lds_dwordx4 v134, s[0:1]
	s_add_u32 s78, s42, 0x80
	s_addc_u32 s79, s43, 0
	s_mov_b32 m0, s51
	s_nop 0
	global_load_lds_dwordx4 v128, s[78:79]
	s_mov_b32 m0, s52
	s_nop 0
	global_load_lds_dwordx4 v132, s[78:79]
	s_waitcnt vmcnt(8)
	s_waitcnt lgkmcnt(0)
	s_barrier
	s_setprio 1
	v_mfma_f32_16x16x32_bf16 v[60:63], v[144:147], v[184:187], v[60:63]
	v_mfma_f32_16x16x32_bf16 v[56:59], v[160:163], v[184:187], v[56:59]
	v_mfma_f32_16x16x32_bf16 v[44:47], v[144:147], v[192:195], v[44:47]
	v_mfma_f32_16x16x32_bf16 v[40:43], v[160:163], v[192:195], v[40:43]
	v_mfma_f32_16x16x32_bf16 v[28:31], v[144:147], v[200:203], v[28:31]
	v_mfma_f32_16x16x32_bf16 v[24:27], v[160:163], v[200:203], v[24:27]
	v_mfma_f32_16x16x32_bf16 v[12:15], v[144:147], v[208:211], v[12:15]
	v_mfma_f32_16x16x32_bf16 v[8:11], v[160:163], v[208:211], v[8:11]
	v_mfma_f32_16x16x32_bf16 v[60:63], v[156:159], v[188:191], v[60:63]
	v_mfma_f32_16x16x32_bf16 v[56:59], v[164:167], v[188:191], v[56:59]
	v_mfma_f32_16x16x32_bf16 v[44:47], v[156:159], v[196:199], v[44:47]
	v_mfma_f32_16x16x32_bf16 v[40:43], v[164:167], v[196:199], v[40:43]
	v_mfma_f32_16x16x32_bf16 v[28:31], v[156:159], v[204:207], v[28:31]
	v_mfma_f32_16x16x32_bf16 v[24:27], v[164:167], v[204:207], v[24:27]
	v_mfma_f32_16x16x32_bf16 v[12:15], v[156:159], v[212:215], v[12:15]
	v_mfma_f32_16x16x32_bf16 v[8:11], v[164:167], v[212:215], v[8:11]
	v_mfma_f32_16x16x32_bf16 v[52:55], v[168:171], v[184:187], v[52:55]
	v_mfma_f32_16x16x32_bf16 v[48:51], v[176:179], v[184:187], v[48:51]
	v_mfma_f32_16x16x32_bf16 v[36:39], v[168:171], v[192:195], v[36:39]
	v_mfma_f32_16x16x32_bf16 v[32:35], v[176:179], v[192:195], v[32:35]
	v_mfma_f32_16x16x32_bf16 v[20:23], v[168:171], v[200:203], v[20:23]
	v_mfma_f32_16x16x32_bf16 v[16:19], v[176:179], v[200:203], v[16:19]
	v_mfma_f32_16x16x32_bf16 v[4:7], v[168:171], v[208:211], v[4:7]
	v_mfma_f32_16x16x32_bf16 v[0:3], v[176:179], v[208:211], v[0:3]
	v_mfma_f32_16x16x32_bf16 v[52:55], v[172:175], v[188:191], v[52:55]
	v_mfma_f32_16x16x32_bf16 v[48:51], v[180:183], v[188:191], v[48:51]
	v_mfma_f32_16x16x32_bf16 v[36:39], v[172:175], v[196:199], v[36:39]
	v_mfma_f32_16x16x32_bf16 v[32:35], v[180:183], v[196:199], v[32:35]
	v_mfma_f32_16x16x32_bf16 v[20:23], v[172:175], v[204:207], v[20:23]
	v_mfma_f32_16x16x32_bf16 v[16:19], v[180:183], v[204:207], v[16:19]
	v_mfma_f32_16x16x32_bf16 v[4:7], v[172:175], v[212:215], v[4:7]
	v_mfma_f32_16x16x32_bf16 v[0:3], v[180:183], v[212:215], v[0:3]
	s_setprio 0
	s_barrier
	s_add_i32 s62, s62, 2
	s_add_u32 s38, s38, 0x100
	s_addc_u32 s39, s39, 0
	s_add_u32 s58, s58, 0x100
	s_addc_u32 s59, s59, 0
	s_cmp_gt_u32 s62, 13
	s_cbranch_scc0 .LBB0_2016
	s_and_b64 vcc, exec, s[18:19]
	s_cbranch_vccz .LBB0_2019
	s_barrier

; #define PG8_STAGE(bufoff, gbase, voff) do { _Pragma("unroll") for (int _i = 0; _i < 2; ++_i) \
;         __builtin_amdgcn_global_load_lds((const unsigned*)((const char*)(gbase) + (voff)[_i]), (PG8_LAS unsigned*)(lds + (bufoff) + ldsw + _i * 8192), 16, 0, 0); } while (0)
; #define PG8_LDA(dst, b, h) do { _Pragma("unroll") for (int m = 0; m < 4; ++m) _Pragma("unroll") for (int k = 0; k < 2; ++k) dst[m][k] = *(const PG8_LAS bf16x8*)(lds + PG8_SA(b, h) + aoff + m * 2048 + k * 1024); } while (0)
; #define PG8_LDB(dst, b, h) do { _Pragma("unroll") for (int n = 0; n < 2; ++n) _Pragma("unroll") for (int k = 0; k < 2; ++k) dst[n][k] = *(const PG8_LAS bf16x8*)(lds + PG8_SB(b, h) + boff + n * 2048 + k * 1024); } while (0)
; #define PG8_MMA(ai, bj, At, Bt) do { __builtin_amdgcn_s_setprio(1); _Pragma("unroll") for (int m = 0; m < 4; ++m) _Pragma("unroll") for (int n = 0; n < 2; ++n) _Pragma("unroll") for (int k = 0; k < 2; ++k) \
;         acc[ai][bj][m][n] = __builtin_amdgcn_mfma_f32_16x16x32_bf16(Bt[n][k], At[m][k], acc[ai][bj][m][n], 0, 0, 0); __builtin_amdgcn_s_setprio(0); } while (0)
; #define PG8_WAIT_V(n) asm volatile("s_waitcnt vmcnt(" #n ")" ::: "memory")
; #define PG8_WAIT_L(n) asm volatile("s_waitcnt lgkmcnt(" #n ")" ::: "memory")
; template <class Epi, class Sched, bool ALIGN_EPI = false, bool SP2 = false>
; __device__ __forceinline__ void gemm_phase(PG8_LAS unsigned char* lds, const Gemm g, const Sched& S, const Epi& E, int wv) {
;     ...
;             const bool last = (t == nt - 2);
;             const char* a1 = cA + (size_t)(t + 1) * kstep;
;             const char* a2 = last ? nA : cA + (size_t)(t + 2) * kstep; const char* b2 = last ? nB : cB + (size_t)(t + 2) * kstep;
;             const char* a3 = a2 + kstep; const char* b3 = b2 + kstep;
;             if (last && has_next) S.a_ready(nxt);
;             if constexpr (SP2) {
;             PG8_LDB(B0, 0, 0); PG8_LDB(B1, 0, 1); PG8_SCHED; PG8_LDA(At, 0, 0); PG8_STAGE(PG8_SA(1, 1), a1 + hstepA, voffA);
;             PG8_WAIT_V(8); PG8_WAIT_L(0); PG8_BAR; PG8_MMA(0, 0, At, B0); PG8_MMA(0, 1, At, B1); PG8_BAR; PG8_SCHED;
;             PG8_LDA(At, 0, 1); PG8_STAGE(PG8_SB(0, 0), b2, voffB); PG8_STAGE(PG8_SB(0, 1), b2 + hstepB, voffB); PG8_STAGE(PG8_SA(0, 0), a2, voffA);
;             PG8_WAIT_V(8); PG8_WAIT_L(0); PG8_BAR; PG8_MMA(1, 0, At, B0); PG8_MMA(1, 1, At, B1); PG8_BAR; PG8_SCHED;
.LBB0_2067:
	ds_read_b128 v[144:147], v155
	ds_read_b128 v[148:151], v155 offset:1024
	ds_read_b128 v[160:163], v155 offset:2048
	ds_read_b128 v[164:167], v155 offset:3072
	ds_read_b128 v[168:171], v156
	ds_read_b128 v[172:175], v156 offset:1024
	ds_read_b128 v[176:179], v156 offset:2048
	ds_read_b128 v[180:183], v156 offset:3072
	s_add_u32 s0, s42, 0xfffc0080
	s_addc_u32 s1, s43, -1
	s_cmp_eq_u32 s71, 12
	s_cselect_b32 s47, s37, s1
	s_cselect_b32 s46, s67, s0
	s_cselect_b32 s45, s29, s70
	s_cselect_b32 s44, s68, s69
	s_add_i32 m0, s52, 0xc000
	ds_read_b128 v[184:187], v157
	ds_read_b128 v[188:191], v157 offset:1024
	ds_read_b128 v[192:195], v157 offset:2048
	ds_read_b128 v[196:199], v157 offset:3072
	ds_read_b128 v[200:203], v157 offset:4096
	ds_read_b128 v[204:207], v157 offset:5120
	ds_read_b128 v[208:211], v157 offset:6144
	ds_read_b128 v[212:215], v157 offset:7168
	global_load_lds_dwordx4 v136, s[42:43]
	s_add_i32 m0, s52, 0xe000
	s_nop 0
	global_load_lds_dwordx4 v138, s[42:43]
	s_waitcnt vmcnt(8)
	s_waitcnt lgkmcnt(0)
	s_barrier
	s_setprio 1
	v_mfma_f32_16x16x32_bf16 v[124:127], v[144:147], v[184:187], v[124:127]
	v_mfma_f32_16x16x32_bf16 v[120:123], v[160:163], v[184:187], v[120:123]
	v_mfma_f32_16x16x32_bf16 v[108:111], v[144:147], v[192:195], v[108:111]
	v_mfma_f32_16x16x32_bf16 v[104:107], v[160:163], v[192:195], v[104:107]
	v_mfma_f32_16x16x32_bf16 v[92:95], v[144:147], v[200:203], v[92:95]
	v_mfma_f32_16x16x32_bf16 v[88:91], v[160:163], v[200:203], v[88:91]
	v_mfma_f32_16x16x32_bf16 v[76:79], v[144:147], v[208:211], v[76:79]
	v_mfma_f32_16x16x32_bf16 v[72:75], v[160:163], v[208:211], v[72:75]
	v_mfma_f32_16x16x32_bf16 v[124:127], v[148:151], v[188:191], v[124:127]
	v_mfma_f32_16x16x32_bf16 v[120:123], v[164:167], v[188:191], v[120:123]
	v_mfma_f32_16x16x32_bf16 v[108:111], v[148:151], v[196:199], v[108:111]
	v_mfma_f32_16x16x32_bf16 v[104:107], v[164:167], v[196:199], v[104:107]
	v_mfma_f32_16x16x32_bf16 v[92:95], v[148:151], v[204:207], v[92:95]
	v_mfma_f32_16x16x32_bf16 v[88:91], v[164:167], v[204:207], v[88:91]
	v_mfma_f32_16x16x32_bf16 v[76:79], v[148:151], v[212:215], v[76:79]
	v_mfma_f32_16x16x32_bf16 v[72:75], v[164:167], v[212:215], v[72:75]
	v_mfma_f32_16x16x32_bf16 v[116:119], v[168:171], v[184:187], v[116:119]
	v_mfma_f32_16x16x32_bf16 v[112:115], v[176:179], v[184:187], v[112:115]
	v_mfma_f32_16x16x32_bf16 v[100:103], v[168:171], v[192:195], v[100:103]
	v_mfma_f32_16x16x32_bf16 v[96:99], v[176:179], v[192:195], v[96:99]
	v_mfma_f32_16x16x32_bf16 v[84:87], v[168:171], v[200:203], v[84:87]
	v_mfma_f32_16x16x32_bf16 v[80:83], v[176:179], v[200:203], v[80:83]
	v_mfma_f32_16x16x32_bf16 v[68:71], v[168:171], v[208:211], v[68:71]
	v_mfma_f32_16x16x32_bf16 v[64:67], v[176:179], v[208:211], v[64:67]
	v_mfma_f32_16x16x32_bf16 v[116:119], v[172:175], v[188:191], v[116:119]
	v_mfma_f32_16x16x32_bf16 v[112:115], v[180:183], v[188:191], v[112:115]
	v_mfma_f32_16x16x32_bf16 v[100:103], v[172:175], v[196:199], v[100:103]
	v_mfma_f32_16x16x32_bf16 v[96:99], v[180:183], v[196:199], v[96:99]
	v_mfma_f32_16x16x32_bf16 v[84:87], v[172:175], v[204:207], v[84:87]
	v_mfma_f32_16x16x32_bf16 v[80:83], v[180:183], v[204:207], v[80:83]
	v_mfma_f32_16x16x32_bf16 v[68:71], v[172:175], v[212:215], v[68:71]
	v_mfma_f32_16x16x32_bf16 v[64:67], v[180:183], v[212:215], v[64:67]
	s_setprio 0
	s_barrier
	s_add_i32 s0, s60, s51
	s_mov_b32 m0, s0
	ds_read_b128 v[184:187], v157 offset:16384
	ds_read_b128 v[188:191], v157 offset:17408
	ds_read_b128 v[192:195], v157 offset:18432
	ds_read_b128 v[196:199], v157 offset:19456
	ds_read_b128 v[200:203], v157 offset:20480
	ds_read_b128 v[204:207], v157 offset:21504
	ds_read_b128 v[208:211], v157 offset:22528
	ds_read_b128 v[212:215], v157 offset:23552
	global_load_lds_dwordx4 v130, s[44:45]
	s_add_i32 m0, s0, 0x2000
	s_add_u32 s0, s44, 0x40000
	s_addc_u32 s1, s45, 0
	s_add_i32 s72, s61, s51
	global_load_lds_dwordx4 v134, s[44:45]
	s_mov_b32 m0, s72
	s_nop 0
	global_load_lds_dwordx4 v130, s[0:1]
	s_add_i32 m0, s72, 0x2000
	s_nop 0
	global_load_lds_dwordx4 v134, s[0:1]
	s_mov_b32 m0, s52
	s_nop 0
	global_load_lds_dwordx4 v128, s[46:47]
	s_mov_b32 m0, s53
	s_nop 0
	global_load_lds_dwordx4 v132, s[46:47]
	s_waitcnt vmcnt(8)
	s_waitcnt lgkmcnt(0)
	s_barrier
	s_setprio 1
	v_mfma_f32_16x16x32_bf16 v[60:63], v[144:147], v[184:187], v[60:63]
	v_mfma_f32_16x16x32_bf16 v[56:59], v[160:163], v[184:187], v[56:59]
	v_mfma_f32_16x16x32_bf16 v[44:47], v[144:147], v[192:195], v[44:47]
	v_mfma_f32_16x16x32_bf16 v[40:43], v[160:163], v[192:195], v[40:43]
	v_mfma_f32_16x16x32_bf16 v[28:31], v[144:147], v[200:203], v[28:31]
	v_mfma_f32_16x16x32_bf16 v[24:27], v[160:163], v[200:203], v[24:27]
	v_mfma_f32_16x16x32_bf16 v[12:15], v[144:147], v[208:211], v[12:15]
	v_mfma_f32_16x16x32_bf16 v[8:11], v[160:163], v[208:211], v[8:11]
	v_mfma_f32_16x16x32_bf16 v[60:63], v[148:151], v[188:191], v[60:63]
	v_mfma_f32_16x16x32_bf16 v[56:59], v[164:167], v[188:191], v[56:59]
	v_mfma_f32_16x16x32_bf16 v[44:47], v[148:151], v[196:199], v[44:47]
	v_mfma_f32_16x16x32_bf16 v[40:43], v[164:167], v[196:199], v[40:43]
	v_mfma_f32_16x16x32_bf16 v[28:31], v[148:151], v[204:207], v[28:31]
	v_mfma_f32_16x16x32_bf16 v[24:27], v[164:167], v[204:207], v[24:27]
	v_mfma_f32_16x16x32_bf16 v[12:15], v[148:151], v[212:215], v[12:15]
	v_mfma_f32_16x16x32_bf16 v[8:11], v[164:167], v[212:215], v[8:11]
	v_mfma_f32_16x16x32_bf16 v[52:55], v[168:171], v[184:187], v[52:55]
	v_mfma_f32_16x16x32_bf16 v[48:51], v[176:179], v[184:187], v[48:51]
	v_mfma_f32_16x16x32_bf16 v[36:39], v[168:171], v[192:195], v[36:39]
	v_mfma_f32_16x16x32_bf16 v[32:35], v[176:179], v[192:195], v[32:35]
	v_mfma_f32_16x16x32_bf16 v[20:23], v[168:171], v[200:203], v[20:23]
	v_mfma_f32_16x16x32_bf16 v[16:19], v[176:179], v[200:203], v[16:19]
	v_mfma_f32_16x16x32_bf16 v[4:7], v[168:171], v[208:211], v[4:7]
	v_mfma_f32_16x16x32_bf16 v[0:3], v[176:179], v[208:211], v[0:3]
	v_mfma_f32_16x16x32_bf16 v[52:55], v[172:175], v[188:191], v[52:55]
	v_mfma_f32_16x16x32_bf16 v[48:51], v[180:183], v[188:191], v[48:51]
	v_mfma_f32_16x16x32_bf16 v[36:39], v[172:175], v[196:199], v[36:39]
	v_mfma_f32_16x16x32_bf16 v[32:35], v[180:183], v[196:199], v[32:35]
	v_mfma_f32_16x16x32_bf16 v[20:23], v[172:175], v[204:207], v[20:23]
	v_mfma_f32_16x16x32_bf16 v[16:19], v[180:183], v[204:207], v[16:19]
	v_mfma_f32_16x16x32_bf16 v[4:7], v[172:175], v[212:215], v[4:7]
	v_mfma_f32_16x16x32_bf16 v[0:3], v[180:183], v[212:215], v[0:3]
	s_setprio 0
	s_barrier
; #define PG8_STAGE(bufoff, gbase, voff) do { _Pragma("unroll") for (int _i = 0; _i < 2; ++_i) \
;         __builtin_amdgcn_global_load_lds((const unsigned*)((const char*)(gbase) + (voff)[_i]), (PG8_LAS unsigned*)(lds + (bufoff) + ldsw + _i * 8192), 16, 0, 0); } while (0)
; #define PG8_LDA(dst, b, h) do { _Pragma("unroll") for (int m = 0; m < 4; ++m) _Pragma("unroll") for (int k = 0; k < 2; ++k) dst[m][k] = *(const PG8_LAS bf16x8*)(lds + PG8_SA(b, h) + aoff + m * 2048 + k * 1024); } while (0)
; #define PG8_LDB(dst, b, h) do { _Pragma("unroll") for (int n = 0; n < 2; ++n) _Pragma("unroll") for (int k = 0; k < 2; ++k) dst[n][k] = *(const PG8_LAS bf16x8*)(lds + PG8_SB(b, h) + boff + n * 2048 + k * 1024); } while (0)
; #define PG8_MMA(ai, bj, At, Bt) do { __builtin_amdgcn_s_setprio(1); _Pragma("unroll") for (int m = 0; m < 4; ++m) _Pragma("unroll") for (int n = 0; n < 2; ++n) _Pragma("unroll") for (int k = 0; k < 2; ++k) \
;         acc[ai][bj][m][n] = __builtin_amdgcn_mfma_f32_16x16x32_bf16(Bt[n][k], At[m][k], acc[ai][bj][m][n], 0, 0, 0); __builtin_amdgcn_s_setprio(0); } while (0)
; #define PG8_WAIT_V(n) asm volatile("s_waitcnt vmcnt(" #n ")" ::: "memory")
; #define PG8_WAIT_L(n) asm volatile("s_waitcnt lgkmcnt(" #n ")" ::: "memory")
; #define PG8_BAR __builtin_amdgcn_s_barrier()
; #define PG8_SCHED __builtin_amdgcn_sched_barrier(0)
; template <class Epi, class Sched, bool ALIGN_EPI = false, bool SP2 = false>
; __device__ __forceinline__ void gemm_phase(PG8_LAS unsigned char* lds, const Gemm g, const Sched& S, const Epi& E, int wv) {
;     ...
;             PG8_LDB(B0, 1, 0); PG8_LDB(B1, 1, 1); PG8_SCHED; PG8_LDA(At, 1, 0); PG8_STAGE(PG8_SA(0, 1), a2 + hstepA, voffA);
;             PG8_WAIT_V(8); PG8_WAIT_L(0); PG8_BAR; PG8_MMA(0, 0, At, B0); PG8_MMA(0, 1, At, B1); PG8_BAR; PG8_SCHED;
;             PG8_LDA(At, 1, 1); PG8_STAGE(PG8_SB(1, 0), b3, voffB); PG8_STAGE(PG8_SB(1, 1), b3 + hstepB, voffB); PG8_STAGE(PG8_SA(1, 0), a3, voffA);
;             PG8_WAIT_V(8); PG8_WAIT_L(0); PG8_BAR; PG8_MMA(1, 0, At, B0); PG8_MMA(1, 1, At, B1); PG8_BAR; PG8_SCHED;
	s_add_i32 s72, 0, 0x18000
	v_add_u32_e32 v159, s72, v153
	s_add_i32 s73, 0, 0x1c000
	ds_read_b128 v[144:147], v159
	ds_read_b128 v[148:151], v159 offset:1024
	ds_read_b128 v[160:163], v159 offset:2048
	ds_read_b128 v[164:167], v159 offset:3072
	v_add_u32_e32 v159, s73, v153
	ds_read_b128 v[168:171], v159
	ds_read_b128 v[172:175], v159 offset:1024
	ds_read_b128 v[176:179], v159 offset:2048
	ds_read_b128 v[180:183], v159 offset:3072
	s_add_u32 s0, s46, 0x40000
	s_addc_u32 s1, s47, 0
	s_mov_b32 m0, s54
	ds_read_b128 v[184:187], v157 offset:32768
	ds_read_b128 v[188:191], v157 offset:33792
	ds_read_b128 v[192:195], v157 offset:34816
	ds_read_b128 v[196:199], v157 offset:35840
	ds_read_b128 v[200:203], v157 offset:36864
	ds_read_b128 v[204:207], v157 offset:37888
	ds_read_b128 v[208:211], v157 offset:38912
	ds_read_b128 v[212:215], v157 offset:39936
	global_load_lds_dwordx4 v128, s[0:1]
	s_mov_b32 m0, s55
	s_nop 0
	global_load_lds_dwordx4 v132, s[0:1]
	s_waitcnt vmcnt(8)
	s_waitcnt lgkmcnt(0)
	s_barrier
	s_setprio 1
	v_mfma_f32_16x16x32_bf16 v[124:127], v[144:147], v[184:187], v[124:127]
	v_mfma_f32_16x16x32_bf16 v[120:123], v[160:163], v[184:187], v[120:123]
	v_mfma_f32_16x16x32_bf16 v[108:111], v[144:147], v[192:195], v[108:111]
	v_mfma_f32_16x16x32_bf16 v[104:107], v[160:163], v[192:195], v[104:107]
	v_mfma_f32_16x16x32_bf16 v[92:95], v[144:147], v[200:203], v[92:95]
	v_mfma_f32_16x16x32_bf16 v[88:91], v[160:163], v[200:203], v[88:91]
	v_mfma_f32_16x16x32_bf16 v[76:79], v[144:147], v[208:211], v[76:79]
	v_mfma_f32_16x16x32_bf16 v[72:75], v[160:163], v[208:211], v[72:75]
	v_mfma_f32_16x16x32_bf16 v[124:127], v[148:151], v[188:191], v[124:127]
	v_mfma_f32_16x16x32_bf16 v[120:123], v[164:167], v[188:191], v[120:123]
	v_mfma_f32_16x16x32_bf16 v[108:111], v[148:151], v[196:199], v[108:111]
	v_mfma_f32_16x16x32_bf16 v[104:107], v[164:167], v[196:199], v[104:107]
	v_mfma_f32_16x16x32_bf16 v[92:95], v[148:151], v[204:207], v[92:95]
	v_mfma_f32_16x16x32_bf16 v[88:91], v[164:167], v[204:207], v[88:91]
	v_mfma_f32_16x16x32_bf16 v[76:79], v[148:151], v[212:215], v[76:79]
	v_mfma_f32_16x16x32_bf16 v[72:75], v[164:167], v[212:215], v[72:75]
	v_mfma_f32_16x16x32_bf16 v[116:119], v[168:171], v[184:187], v[116:119]
	v_mfma_f32_16x16x32_bf16 v[112:115], v[176:179], v[184:187], v[112:115]
	v_mfma_f32_16x16x32_bf16 v[100:103], v[168:171], v[192:195], v[100:103]
	v_mfma_f32_16x16x32_bf16 v[96:99], v[176:179], v[192:195], v[96:99]
	v_mfma_f32_16x16x32_bf16 v[84:87], v[168:171], v[200:203], v[84:87]
	v_mfma_f32_16x16x32_bf16 v[80:83], v[176:179], v[200:203], v[80:83]
	v_mfma_f32_16x16x32_bf16 v[68:71], v[168:171], v[208:211], v[68:71]
	v_mfma_f32_16x16x32_bf16 v[64:67], v[176:179], v[208:211], v[64:67]
	v_mfma_f32_16x16x32_bf16 v[116:119], v[172:175], v[188:191], v[116:119]
	v_mfma_f32_16x16x32_bf16 v[112:115], v[180:183], v[188:191], v[112:115]
	v_mfma_f32_16x16x32_bf16 v[100:103], v[172:175], v[196:199], v[100:103]
	v_mfma_f32_16x16x32_bf16 v[96:99], v[180:183], v[196:199], v[96:99]
	v_mfma_f32_16x16x32_bf16 v[84:87], v[172:175], v[204:207], v[84:87]
	v_mfma_f32_16x16x32_bf16 v[80:83], v[180:183], v[204:207], v[80:83]
	v_mfma_f32_16x16x32_bf16 v[68:71], v[172:175], v[212:215], v[68:71]
	v_mfma_f32_16x16x32_bf16 v[64:67], v[180:183], v[212:215], v[64:67]
	s_setprio 0
	s_barrier
	s_add_i32 s0, s72, s51
	s_add_u32 s76, s44, 0x80
	s_addc_u32 s77, s45, 0
	s_mov_b32 m0, s0
	ds_read_b128 v[184:187], v157 offset:49152
	ds_read_b128 v[188:191], v157 offset:50176
	ds_read_b128 v[192:195], v157 offset:51200
	ds_read_b128 v[196:199], v157 offset:52224
	ds_read_b128 v[200:203], v157 offset:53248
	ds_read_b128 v[204:207], v157 offset:54272
	ds_read_b128 v[208:211], v157 offset:55296
	ds_read_b128 v[212:215], v157 offset:56320
	global_load_lds_dwordx4 v130, s[76:77]
	s_add_i32 m0, s0, 0x2000
	s_add_u32 s0, s44, 0x40080
	s_addc_u32 s1, s45, 0
	s_add_i32 s44, s73, s51
	global_load_lds_dwordx4 v134, s[76:77]
	s_mov_b32 m0, s44
	s_nop 0
	global_load_lds_dwordx4 v130, s[0:1]
	s_add_i32 m0, s44, 0x2000
	s_nop 0
	global_load_lds_dwordx4 v134, s[0:1]
	s_add_u32 s78, s46, 0x80
	s_addc_u32 s79, s47, 0
	s_mov_b32 m0, s57
	s_nop 0
	global_load_lds_dwordx4 v128, s[78:79]
	s_mov_b32 m0, s58
	s_nop 0
	global_load_lds_dwordx4 v132, s[78:79]
	s_waitcnt vmcnt(8)
	s_waitcnt lgkmcnt(0)
	s_barrier
	s_setprio 1
	v_mfma_f32_16x16x32_bf16 v[60:63], v[144:147], v[184:187], v[60:63]
	v_mfma_f32_16x16x32_bf16 v[56:59], v[160:163], v[184:187], v[56:59]
	v_mfma_f32_16x16x32_bf16 v[44:47], v[144:147], v[192:195], v[44:47]
	v_mfma_f32_16x16x32_bf16 v[40:43], v[160:163], v[192:195], v[40:43]
	v_mfma_f32_16x16x32_bf16 v[28:31], v[144:147], v[200:203], v[28:31]
	v_mfma_f32_16x16x32_bf16 v[24:27], v[160:163], v[200:203], v[24:27]
	v_mfma_f32_16x16x32_bf16 v[12:15], v[144:147], v[208:211], v[12:15]
	v_mfma_f32_16x16x32_bf16 v[8:11], v[160:163], v[208:211], v[8:11]
	v_mfma_f32_16x16x32_bf16 v[60:63], v[148:151], v[188:191], v[60:63]
	v_mfma_f32_16x16x32_bf16 v[56:59], v[164:167], v[188:191], v[56:59]
	v_mfma_f32_16x16x32_bf16 v[44:47], v[148:151], v[196:199], v[44:47]
	v_mfma_f32_16x16x32_bf16 v[40:43], v[164:167], v[196:199], v[40:43]
	v_mfma_f32_16x16x32_bf16 v[28:31], v[148:151], v[204:207], v[28:31]
	v_mfma_f32_16x16x32_bf16 v[24:27], v[164:167], v[204:207], v[24:27]
	v_mfma_f32_16x16x32_bf16 v[12:15], v[148:151], v[212:215], v[12:15]
	v_mfma_f32_16x16x32_bf16 v[8:11], v[164:167], v[212:215], v[8:11]
	v_mfma_f32_16x16x32_bf16 v[52:55], v[168:171], v[184:187], v[52:55]
	v_mfma_f32_16x16x32_bf16 v[48:51], v[176:179], v[184:187], v[48:51]
	v_mfma_f32_16x16x32_bf16 v[36:39], v[168:171], v[192:195], v[36:39]
	v_mfma_f32_16x16x32_bf16 v[32:35], v[176:179], v[192:195], v[32:35]
	v_mfma_f32_16x16x32_bf16 v[20:23], v[168:171], v[200:203], v[20:23]
	v_mfma_f32_16x16x32_bf16 v[16:19], v[176:179], v[200:203], v[16:19]
	v_mfma_f32_16x16x32_bf16 v[4:7], v[168:171], v[208:211], v[4:7]
	v_mfma_f32_16x16x32_bf16 v[0:3], v[176:179], v[208:211], v[0:3]
	v_mfma_f32_16x16x32_bf16 v[52:55], v[172:175], v[188:191], v[52:55]
	v_mfma_f32_16x16x32_bf16 v[48:51], v[180:183], v[188:191], v[48:51]
	v_mfma_f32_16x16x32_bf16 v[36:39], v[172:175], v[196:199], v[36:39]
	v_mfma_f32_16x16x32_bf16 v[32:35], v[180:183], v[196:199], v[32:35]
	v_mfma_f32_16x16x32_bf16 v[20:23], v[172:175], v[204:207], v[20:23]
	v_mfma_f32_16x16x32_bf16 v[16:19], v[180:183], v[204:207], v[16:19]
	v_mfma_f32_16x16x32_bf16 v[4:7], v[172:175], v[212:215], v[4:7]
	v_mfma_f32_16x16x32_bf16 v[0:3], v[180:183], v[212:215], v[0:3]
	s_setprio 0
	s_barrier
	s_add_i32 s71, s71, 2
	s_add_u32 s42, s42, 0x100
	s_addc_u32 s43, s43, 0
	s_add_u32 s69, s69, 0x100
	s_addc_u32 s70, s70, 0
	s_cmp_gt_u32 s71, 13
	s_cbranch_scc0 .LBB0_2067
	s_and_b64 vcc, exec, s[18:19]
	s_cbranch_vccz .LBB0_2070
	s_barrier

; #define PG8_STAGE(bufoff, gbase, voff) do { _Pragma("unroll") for (int _i = 0; _i < 2; ++_i) \
;         __builtin_amdgcn_global_load_lds((const unsigned*)((const char*)(gbase) + (voff)[_i]), (PG8_LAS unsigned*)(lds + (bufoff) + ldsw + _i * 8192), 16, 0, 0); } while (0)
; #define PG8_LDA(dst, b, h) do { _Pragma("unroll") for (int m = 0; m < 4; ++m) _Pragma("unroll") for (int k = 0; k < 2; ++k) dst[m][k] = *(const PG8_LAS bf16x8*)(lds + PG8_SA(b, h) + aoff + m * 2048 + k * 1024); } while (0)
; #define PG8_LDB(dst, b, h) do { _Pragma("unroll") for (int n = 0; n < 2; ++n) _Pragma("unroll") for (int k = 0; k < 2; ++k) dst[n][k] = *(const PG8_LAS bf16x8*)(lds + PG8_SB(b, h) + boff + n * 2048 + k * 1024); } while (0)
; #define PG8_MMA(ai, bj, At, Bt) do { __builtin_amdgcn_s_setprio(1); _Pragma("unroll") for (int m = 0; m < 4; ++m) _Pragma("unroll") for (int n = 0; n < 2; ++n) _Pragma("unroll") for (int k = 0; k < 2; ++k) \
;         acc[ai][bj][m][n] = __builtin_amdgcn_mfma_f32_16x16x32_bf16(Bt[n][k], At[m][k], acc[ai][bj][m][n], 0, 0, 0); __builtin_amdgcn_s_setprio(0); } while (0)
; #define PG8_WAIT_V(n) asm volatile("s_waitcnt vmcnt(" #n ")" ::: "memory")
; #define PG8_WAIT_L(n) asm volatile("s_waitcnt lgkmcnt(" #n ")" ::: "memory")
; template <class Epi, class Sched, bool ALIGN_EPI = false, bool SP2 = false>
; __device__ __forceinline__ void gemm_phase(PG8_LAS unsigned char* lds, const Gemm g, const Sched& S, const Epi& E, int wv) {
;     ...
;             const bool last = (t == nt - 2);
;             const char* a1 = cA + (size_t)(t + 1) * kstep;
;             const char* a2 = last ? nA : cA + (size_t)(t + 2) * kstep; const char* b2 = last ? nB : cB + (size_t)(t + 2) * kstep;
;             const char* a3 = a2 + kstep; const char* b3 = b2 + kstep;
;             if (last && has_next) S.a_ready(nxt);
;             if constexpr (SP2) {
;             PG8_LDB(B0, 0, 0); PG8_LDB(B1, 0, 1); PG8_SCHED; PG8_LDA(At, 0, 0); PG8_STAGE(PG8_SA(1, 1), a1 + hstepA, voffA);
;             PG8_WAIT_V(8); PG8_WAIT_L(0); PG8_BAR; PG8_MMA(0, 0, At, B0); PG8_MMA(0, 1, At, B1); PG8_BAR; PG8_SCHED;
;             PG8_LDA(At, 0, 1); PG8_STAGE(PG8_SB(0, 0), b2, voffB); PG8_STAGE(PG8_SB(0, 1), b2 + hstepB, voffB); PG8_STAGE(PG8_SA(0, 0), a2, voffA);
;             PG8_WAIT_V(8); PG8_WAIT_L(0); PG8_BAR; PG8_MMA(1, 0, At, B0); PG8_MMA(1, 1, At, B1); PG8_BAR; PG8_SCHED;
.LBB0_2102:
	ds_read_b128 v[144:147], v153
	ds_read_b128 v[156:159], v153 offset:1024
	ds_read_b128 v[160:163], v153 offset:2048
	ds_read_b128 v[164:167], v153 offset:3072
	ds_read_b128 v[168:171], v154
	ds_read_b128 v[172:175], v154 offset:1024
	ds_read_b128 v[176:179], v154 offset:2048
	ds_read_b128 v[180:183], v154 offset:3072
	s_add_u32 s38, s36, 0xfff00080
	s_addc_u32 s39, s37, -1
	s_cmp_eq_u32 s59, 60
	s_cselect_b32 s41, s23, s39
	s_cselect_b32 s40, s55, s38
	s_cselect_b32 s39, s21, s58
	s_cselect_b32 s38, s56, s57
	s_add_i32 m0, s29, 0xc000
	ds_read_b128 v[184:187], v155
	ds_read_b128 v[188:191], v155 offset:1024
	ds_read_b128 v[192:195], v155 offset:2048
	ds_read_b128 v[196:199], v155 offset:3072
	ds_read_b128 v[200:203], v155 offset:4096
	ds_read_b128 v[204:207], v155 offset:5120
	ds_read_b128 v[208:211], v155 offset:6144
	ds_read_b128 v[212:215], v155 offset:7168
	global_load_lds_dwordx4 v136, s[36:37]
	s_add_i32 m0, s29, 0xe000
	s_nop 0
	global_load_lds_dwordx4 v138, s[36:37]
	s_waitcnt vmcnt(8)
	s_waitcnt lgkmcnt(0)
	s_barrier
	s_setprio 1
	v_mfma_f32_16x16x32_bf16 v[124:127], v[144:147], v[184:187], v[124:127]
	v_mfma_f32_16x16x32_bf16 v[120:123], v[160:163], v[184:187], v[120:123]
	v_mfma_f32_16x16x32_bf16 v[108:111], v[144:147], v[192:195], v[108:111]
	v_mfma_f32_16x16x32_bf16 v[104:107], v[160:163], v[192:195], v[104:107]
	v_mfma_f32_16x16x32_bf16 v[92:95], v[144:147], v[200:203], v[92:95]
	v_mfma_f32_16x16x32_bf16 v[88:91], v[160:163], v[200:203], v[88:91]
	v_mfma_f32_16x16x32_bf16 v[76:79], v[144:147], v[208:211], v[76:79]
	v_mfma_f32_16x16x32_bf16 v[72:75], v[160:163], v[208:211], v[72:75]
	v_mfma_f32_16x16x32_bf16 v[124:127], v[156:159], v[188:191], v[124:127]
	v_mfma_f32_16x16x32_bf16 v[120:123], v[164:167], v[188:191], v[120:123]
	v_mfma_f32_16x16x32_bf16 v[108:111], v[156:159], v[196:199], v[108:111]
	v_mfma_f32_16x16x32_bf16 v[104:107], v[164:167], v[196:199], v[104:107]
	v_mfma_f32_16x16x32_bf16 v[92:95], v[156:159], v[204:207], v[92:95]
	v_mfma_f32_16x16x32_bf16 v[88:91], v[164:167], v[204:207], v[88:91]
	v_mfma_f32_16x16x32_bf16 v[76:79], v[156:159], v[212:215], v[76:79]
	v_mfma_f32_16x16x32_bf16 v[72:75], v[164:167], v[212:215], v[72:75]
	v_mfma_f32_16x16x32_bf16 v[116:119], v[168:171], v[184:187], v[116:119]
	v_mfma_f32_16x16x32_bf16 v[112:115], v[176:179], v[184:187], v[112:115]
	v_mfma_f32_16x16x32_bf16 v[100:103], v[168:171], v[192:195], v[100:103]
	v_mfma_f32_16x16x32_bf16 v[96:99], v[176:179], v[192:195], v[96:99]
	v_mfma_f32_16x16x32_bf16 v[84:87], v[168:171], v[200:203], v[84:87]
	v_mfma_f32_16x16x32_bf16 v[80:83], v[176:179], v[200:203], v[80:83]
	v_mfma_f32_16x16x32_bf16 v[68:71], v[168:171], v[208:211], v[68:71]
	v_mfma_f32_16x16x32_bf16 v[64:67], v[176:179], v[208:211], v[64:67]
	v_mfma_f32_16x16x32_bf16 v[116:119], v[172:175], v[188:191], v[116:119]
	v_mfma_f32_16x16x32_bf16 v[112:115], v[180:183], v[188:191], v[112:115]
	v_mfma_f32_16x16x32_bf16 v[100:103], v[172:175], v[196:199], v[100:103]
	v_mfma_f32_16x16x32_bf16 v[96:99], v[180:183], v[196:199], v[96:99]
	v_mfma_f32_16x16x32_bf16 v[84:87], v[172:175], v[204:207], v[84:87]
	v_mfma_f32_16x16x32_bf16 v[80:83], v[180:183], v[204:207], v[80:83]
	v_mfma_f32_16x16x32_bf16 v[68:71], v[172:175], v[212:215], v[68:71]
	v_mfma_f32_16x16x32_bf16 v[64:67], v[180:183], v[212:215], v[64:67]
	s_setprio 0
	s_barrier
	s_add_i32 s60, s52, s44
	s_mov_b32 m0, s60
	ds_read_b128 v[184:187], v155 offset:16384
	ds_read_b128 v[188:191], v155 offset:17408
	ds_read_b128 v[192:195], v155 offset:18432
	ds_read_b128 v[196:199], v155 offset:19456
	ds_read_b128 v[200:203], v155 offset:20480
	ds_read_b128 v[204:207], v155 offset:21504
	ds_read_b128 v[208:211], v155 offset:22528
	ds_read_b128 v[212:215], v155 offset:23552
	global_load_lds_dwordx4 v130, s[38:39]
	s_add_i32 m0, s60, 0x2000
	s_add_u32 s60, s38, 0x100000
	s_addc_u32 s61, s39, 0
	s_add_i32 s62, s53, s44
	global_load_lds_dwordx4 v134, s[38:39]
	s_mov_b32 m0, s62
	s_add_u32 s82, s40, 0x80
	s_addc_u32 s83, s41, 0
	global_load_lds_dwordx4 v130, s[60:61]
	s_add_i32 m0, s62, 0x2000
	s_nop 0
	global_load_lds_dwordx4 v134, s[60:61]
	s_mov_b32 m0, s29
	s_nop 0
	global_load_lds_dwordx4 v128, s[40:41]
	s_mov_b32 m0, s45
	s_nop 0
	global_load_lds_dwordx4 v132, s[40:41]
	s_waitcnt vmcnt(8)
	s_waitcnt lgkmcnt(0)
	s_barrier
	s_setprio 1
	v_mfma_f32_16x16x32_bf16 v[60:63], v[144:147], v[184:187], v[60:63]
	v_mfma_f32_16x16x32_bf16 v[56:59], v[160:163], v[184:187], v[56:59]
	v_mfma_f32_16x16x32_bf16 v[44:47], v[144:147], v[192:195], v[44:47]
	v_mfma_f32_16x16x32_bf16 v[40:43], v[160:163], v[192:195], v[40:43]
	v_mfma_f32_16x16x32_bf16 v[28:31], v[144:147], v[200:203], v[28:31]
	v_mfma_f32_16x16x32_bf16 v[24:27], v[160:163], v[200:203], v[24:27]
	v_mfma_f32_16x16x32_bf16 v[12:15], v[144:147], v[208:211], v[12:15]
	v_mfma_f32_16x16x32_bf16 v[8:11], v[160:163], v[208:211], v[8:11]
	v_mfma_f32_16x16x32_bf16 v[60:63], v[156:159], v[188:191], v[60:63]
	v_mfma_f32_16x16x32_bf16 v[56:59], v[164:167], v[188:191], v[56:59]
	v_mfma_f32_16x16x32_bf16 v[44:47], v[156:159], v[196:199], v[44:47]
	v_mfma_f32_16x16x32_bf16 v[40:43], v[164:167], v[196:199], v[40:43]
	v_mfma_f32_16x16x32_bf16 v[28:31], v[156:159], v[204:207], v[28:31]
	v_mfma_f32_16x16x32_bf16 v[24:27], v[164:167], v[204:207], v[24:27]
	v_mfma_f32_16x16x32_bf16 v[12:15], v[156:159], v[212:215], v[12:15]
	v_mfma_f32_16x16x32_bf16 v[8:11], v[164:167], v[212:215], v[8:11]
	v_mfma_f32_16x16x32_bf16 v[52:55], v[168:171], v[184:187], v[52:55]
	v_mfma_f32_16x16x32_bf16 v[48:51], v[176:179], v[184:187], v[48:51]
	v_mfma_f32_16x16x32_bf16 v[36:39], v[168:171], v[192:195], v[36:39]
	v_mfma_f32_16x16x32_bf16 v[32:35], v[176:179], v[192:195], v[32:35]
	v_mfma_f32_16x16x32_bf16 v[20:23], v[168:171], v[200:203], v[20:23]
	v_mfma_f32_16x16x32_bf16 v[16:19], v[176:179], v[200:203], v[16:19]
	v_mfma_f32_16x16x32_bf16 v[4:7], v[168:171], v[208:211], v[4:7]
	v_mfma_f32_16x16x32_bf16 v[0:3], v[176:179], v[208:211], v[0:3]
	v_mfma_f32_16x16x32_bf16 v[52:55], v[172:175], v[188:191], v[52:55]
	v_mfma_f32_16x16x32_bf16 v[48:51], v[180:183], v[188:191], v[48:51]
	v_mfma_f32_16x16x32_bf16 v[36:39], v[172:175], v[196:199], v[36:39]
	v_mfma_f32_16x16x32_bf16 v[32:35], v[180:183], v[196:199], v[32:35]
	v_mfma_f32_16x16x32_bf16 v[20:23], v[172:175], v[204:207], v[20:23]
	v_mfma_f32_16x16x32_bf16 v[16:19], v[180:183], v[204:207], v[16:19]
	v_mfma_f32_16x16x32_bf16 v[4:7], v[172:175], v[212:215], v[4:7]
	v_mfma_f32_16x16x32_bf16 v[0:3], v[180:183], v[212:215], v[0:3]
	s_setprio 0
	s_barrier
; #define PG8_STAGE(bufoff, gbase, voff) do { _Pragma("unroll") for (int _i = 0; _i < 2; ++_i) \
;         __builtin_amdgcn_global_load_lds((const unsigned*)((const char*)(gbase) + (voff)[_i]), (PG8_LAS unsigned*)(lds + (bufoff) + ldsw + _i * 8192), 16, 0, 0); } while (0)
; #define PG8_LDA(dst, b, h) do { _Pragma("unroll") for (int m = 0; m < 4; ++m) _Pragma("unroll") for (int k = 0; k < 2; ++k) dst[m][k] = *(const PG8_LAS bf16x8*)(lds + PG8_SA(b, h) + aoff + m * 2048 + k * 1024); } while (0)
; #define PG8_LDB(dst, b, h) do { _Pragma("unroll") for (int n = 0; n < 2; ++n) _Pragma("unroll") for (int k = 0; k < 2; ++k) dst[n][k] = *(const PG8_LAS bf16x8*)(lds + PG8_SB(b, h) + boff + n * 2048 + k * 1024); } while (0)
; #define PG8_MMA(ai, bj, At, Bt) do { __builtin_amdgcn_s_setprio(1); _Pragma("unroll") for (int m = 0; m < 4; ++m) _Pragma("unroll") for (int n = 0; n < 2; ++n) _Pragma("unroll") for (int k = 0; k < 2; ++k) \
;         acc[ai][bj][m][n] = __builtin_amdgcn_mfma_f32_16x16x32_bf16(Bt[n][k], At[m][k], acc[ai][bj][m][n], 0, 0, 0); __builtin_amdgcn_s_setprio(0); } while (0)
; #define PG8_WAIT_V(n) asm volatile("s_waitcnt vmcnt(" #n ")" ::: "memory")
; #define PG8_WAIT_L(n) asm volatile("s_waitcnt lgkmcnt(" #n ")" ::: "memory")
; #define PG8_BAR __builtin_amdgcn_s_barrier()
; #define PG8_SCHED __builtin_amdgcn_sched_barrier(0)
; template <class Epi, class Sched, bool ALIGN_EPI = false, bool SP2 = false>
; __device__ __forceinline__ void gemm_phase(PG8_LAS unsigned char* lds, const Gemm g, const Sched& S, const Epi& E, int wv) {
;     ...
;             PG8_LDB(B0, 1, 0); PG8_LDB(B1, 1, 1); PG8_SCHED; PG8_LDA(At, 1, 0); PG8_STAGE(PG8_SA(0, 1), a2 + hstepA, voffA);
;             PG8_WAIT_V(8); PG8_WAIT_L(0); PG8_BAR; PG8_MMA(0, 0, At, B0); PG8_MMA(0, 1, At, B1); PG8_BAR; PG8_SCHED;
;             PG8_LDA(At, 1, 1); PG8_STAGE(PG8_SB(1, 0), b3, voffB); PG8_STAGE(PG8_SB(1, 1), b3 + hstepB, voffB); PG8_STAGE(PG8_SA(1, 0), a3, voffA);
;             PG8_WAIT_V(8); PG8_WAIT_L(0); PG8_BAR; PG8_MMA(1, 0, At, B0); PG8_MMA(1, 1, At, B1); PG8_BAR; PG8_SCHED;
	s_add_i32 s60, 0, 0x18000
	s_add_i32 s61, 0, 0x1c000
	v_add_u32_e32 v164, s60, v151
	v_add_u32_e32 v180, s61, v151
	ds_read_b128 v[144:147], v164
	ds_read_b128 v[156:159], v164 offset:1024
	ds_read_b128 v[160:163], v164 offset:2048
	ds_read_b128 v[164:167], v164 offset:3072
	ds_read_b128 v[168:171], v180
	ds_read_b128 v[172:175], v180 offset:1024
	ds_read_b128 v[176:179], v180 offset:2048
	ds_read_b128 v[180:183], v180 offset:3072
	s_add_u32 s40, s40, 0x100000
	s_addc_u32 s41, s41, 0
	s_mov_b32 m0, s46
	ds_read_b128 v[184:187], v155 offset:32768
	ds_read_b128 v[188:191], v155 offset:33792
	ds_read_b128 v[192:195], v155 offset:34816
	ds_read_b128 v[196:199], v155 offset:35840
	ds_read_b128 v[200:203], v155 offset:36864
	ds_read_b128 v[204:207], v155 offset:37888
	ds_read_b128 v[208:211], v155 offset:38912
	ds_read_b128 v[212:215], v155 offset:39936
	global_load_lds_dwordx4 v128, s[40:41]
	s_mov_b32 m0, s47
	s_nop 0
	global_load_lds_dwordx4 v132, s[40:41]
	s_waitcnt vmcnt(8)
	s_waitcnt lgkmcnt(0)
	s_barrier
	s_setprio 1
	v_mfma_f32_16x16x32_bf16 v[124:127], v[144:147], v[184:187], v[124:127]
	v_mfma_f32_16x16x32_bf16 v[120:123], v[160:163], v[184:187], v[120:123]
	v_mfma_f32_16x16x32_bf16 v[108:111], v[144:147], v[192:195], v[108:111]
	v_mfma_f32_16x16x32_bf16 v[104:107], v[160:163], v[192:195], v[104:107]
	v_mfma_f32_16x16x32_bf16 v[92:95], v[144:147], v[200:203], v[92:95]
	v_mfma_f32_16x16x32_bf16 v[88:91], v[160:163], v[200:203], v[88:91]
	v_mfma_f32_16x16x32_bf16 v[76:79], v[144:147], v[208:211], v[76:79]
	v_mfma_f32_16x16x32_bf16 v[72:75], v[160:163], v[208:211], v[72:75]
	v_mfma_f32_16x16x32_bf16 v[124:127], v[156:159], v[188:191], v[124:127]
	v_mfma_f32_16x16x32_bf16 v[120:123], v[164:167], v[188:191], v[120:123]
	v_mfma_f32_16x16x32_bf16 v[108:111], v[156:159], v[196:199], v[108:111]
	v_mfma_f32_16x16x32_bf16 v[104:107], v[164:167], v[196:199], v[104:107]
	v_mfma_f32_16x16x32_bf16 v[92:95], v[156:159], v[204:207], v[92:95]
	v_mfma_f32_16x16x32_bf16 v[88:91], v[164:167], v[204:207], v[88:91]
	v_mfma_f32_16x16x32_bf16 v[76:79], v[156:159], v[212:215], v[76:79]
	v_mfma_f32_16x16x32_bf16 v[72:75], v[164:167], v[212:215], v[72:75]
	v_mfma_f32_16x16x32_bf16 v[116:119], v[168:171], v[184:187], v[116:119]
	v_mfma_f32_16x16x32_bf16 v[112:115], v[176:179], v[184:187], v[112:115]
	v_mfma_f32_16x16x32_bf16 v[100:103], v[168:171], v[192:195], v[100:103]
	v_mfma_f32_16x16x32_bf16 v[96:99], v[176:179], v[192:195], v[96:99]
	v_mfma_f32_16x16x32_bf16 v[84:87], v[168:171], v[200:203], v[84:87]
	v_mfma_f32_16x16x32_bf16 v[80:83], v[176:179], v[200:203], v[80:83]
	v_mfma_f32_16x16x32_bf16 v[68:71], v[168:171], v[208:211], v[68:71]
	v_mfma_f32_16x16x32_bf16 v[64:67], v[176:179], v[208:211], v[64:67]
	v_mfma_f32_16x16x32_bf16 v[116:119], v[172:175], v[188:191], v[116:119]
	v_mfma_f32_16x16x32_bf16 v[112:115], v[180:183], v[188:191], v[112:115]
	v_mfma_f32_16x16x32_bf16 v[100:103], v[172:175], v[196:199], v[100:103]
	v_mfma_f32_16x16x32_bf16 v[96:99], v[180:183], v[196:199], v[96:99]
	v_mfma_f32_16x16x32_bf16 v[84:87], v[172:175], v[204:207], v[84:87]
	v_mfma_f32_16x16x32_bf16 v[80:83], v[180:183], v[204:207], v[80:83]
	v_mfma_f32_16x16x32_bf16 v[68:71], v[172:175], v[212:215], v[68:71]
	v_mfma_f32_16x16x32_bf16 v[64:67], v[180:183], v[212:215], v[64:67]
	s_setprio 0
	s_barrier
	s_add_i32 s40, s60, s44
	s_add_u32 s80, s38, 0x80
	s_addc_u32 s81, s39, 0
	s_mov_b32 m0, s40
	ds_read_b128 v[184:187], v155 offset:49152
	ds_read_b128 v[188:191], v155 offset:50176
	ds_read_b128 v[192:195], v155 offset:51200
	ds_read_b128 v[196:199], v155 offset:52224
	ds_read_b128 v[200:203], v155 offset:53248
	ds_read_b128 v[204:207], v155 offset:54272
	ds_read_b128 v[208:211], v155 offset:55296
	ds_read_b128 v[212:215], v155 offset:56320
	global_load_lds_dwordx4 v130, s[80:81]
	s_add_i32 m0, s40, 0x2000
	s_add_u32 s38, s38, 0x100080
	s_addc_u32 s39, s39, 0
	s_add_i32 s40, s61, s44
	global_load_lds_dwordx4 v134, s[80:81]
	s_mov_b32 m0, s40
	s_nop 0
	global_load_lds_dwordx4 v130, s[38:39]
	s_add_i32 m0, s40, 0x2000
	s_nop 0
	global_load_lds_dwordx4 v134, s[38:39]
	s_mov_b32 m0, s49
	s_nop 0
	global_load_lds_dwordx4 v128, s[82:83]
	s_mov_b32 m0, s50
	s_nop 0
	global_load_lds_dwordx4 v132, s[82:83]
	s_waitcnt vmcnt(8)
	s_waitcnt lgkmcnt(0)
	s_barrier
	s_setprio 1
	v_mfma_f32_16x16x32_bf16 v[60:63], v[144:147], v[184:187], v[60:63]
	v_mfma_f32_16x16x32_bf16 v[56:59], v[160:163], v[184:187], v[56:59]
	v_mfma_f32_16x16x32_bf16 v[44:47], v[144:147], v[192:195], v[44:47]
	v_mfma_f32_16x16x32_bf16 v[40:43], v[160:163], v[192:195], v[40:43]
	v_mfma_f32_16x16x32_bf16 v[28:31], v[144:147], v[200:203], v[28:31]
	v_mfma_f32_16x16x32_bf16 v[24:27], v[160:163], v[200:203], v[24:27]
	v_mfma_f32_16x16x32_bf16 v[12:15], v[144:147], v[208:211], v[12:15]
	v_mfma_f32_16x16x32_bf16 v[8:11], v[160:163], v[208:211], v[8:11]
	v_mfma_f32_16x16x32_bf16 v[60:63], v[156:159], v[188:191], v[60:63]
	v_mfma_f32_16x16x32_bf16 v[56:59], v[164:167], v[188:191], v[56:59]
	v_mfma_f32_16x16x32_bf16 v[44:47], v[156:159], v[196:199], v[44:47]
	v_mfma_f32_16x16x32_bf16 v[40:43], v[164:167], v[196:199], v[40:43]
	v_mfma_f32_16x16x32_bf16 v[28:31], v[156:159], v[204:207], v[28:31]
	v_mfma_f32_16x16x32_bf16 v[24:27], v[164:167], v[204:207], v[24:27]
	v_mfma_f32_16x16x32_bf16 v[12:15], v[156:159], v[212:215], v[12:15]
	v_mfma_f32_16x16x32_bf16 v[8:11], v[164:167], v[212:215], v[8:11]
	v_mfma_f32_16x16x32_bf16 v[52:55], v[168:171], v[184:187], v[52:55]
	v_mfma_f32_16x16x32_bf16 v[48:51], v[176:179], v[184:187], v[48:51]
	v_mfma_f32_16x16x32_bf16 v[36:39], v[168:171], v[192:195], v[36:39]
	v_mfma_f32_16x16x32_bf16 v[32:35], v[176:179], v[192:195], v[32:35]
	v_mfma_f32_16x16x32_bf16 v[20:23], v[168:171], v[200:203], v[20:23]
	v_mfma_f32_16x16x32_bf16 v[16:19], v[176:179], v[200:203], v[16:19]
	v_mfma_f32_16x16x32_bf16 v[4:7], v[168:171], v[208:211], v[4:7]
	v_mfma_f32_16x16x32_bf16 v[0:3], v[176:179], v[208:211], v[0:3]
	v_mfma_f32_16x16x32_bf16 v[52:55], v[172:175], v[188:191], v[52:55]
	v_mfma_f32_16x16x32_bf16 v[48:51], v[180:183], v[188:191], v[48:51]
	v_mfma_f32_16x16x32_bf16 v[36:39], v[172:175], v[196:199], v[36:39]
	v_mfma_f32_16x16x32_bf16 v[32:35], v[180:183], v[196:199], v[32:35]
	v_mfma_f32_16x16x32_bf16 v[20:23], v[172:175], v[204:207], v[20:23]
	v_mfma_f32_16x16x32_bf16 v[16:19], v[180:183], v[204:207], v[16:19]
	v_mfma_f32_16x16x32_bf16 v[4:7], v[172:175], v[212:215], v[4:7]
	v_mfma_f32_16x16x32_bf16 v[0:3], v[180:183], v[212:215], v[0:3]
	s_setprio 0
	s_barrier
	s_add_i32 s59, s59, 2
	s_add_u32 s36, s36, 0x100
	s_addc_u32 s37, s37, 0
	s_add_u32 s57, s57, 0x100
	s_addc_u32 s58, s58, 0
	s_cmp_gt_u32 s59, 61
	s_cbranch_scc0 .LBB0_2102
	s_and_b64 vcc, exec, s[6:7]
	s_cbranch_vccz .LBB0_2105
	s_barrier
